# GEMM k-loops: sc1 (L1-bypass) on the LDS-DMA operand loads
# baseline (speedup 1.0000x reference)
.LBB0_114:
	v_mov_b32_e32 v6, v181
	s_ashr_i32 s93, s92, 6
	v_lshrrev_b32_e32 v7, 4, v6
	v_lshlrev_b32_e32 v1, 6, v6
	v_xor_b32_e32 v0, v7, v6
	v_and_b32_e32 v8, 0x3c0, v1
	v_lshlrev_b32_e32 v1, 7, v6
	s_bfe_u32 s94, s92, 0x20006
	s_and_b32 s86, s91, 63
	s_and_b32 s95, s92, 63
	s_and_b32 s21, s93, -4
	v_lshlrev_b32_e32 v0, 3, v0
	v_and_b32_e32 v1, 0xfffffc00, v1
	s_lshl_b32 s20, s86, 19
	s_or_b32 s58, s21, s94
	s_lshl_b32 s21, s95, 19
	v_and_or_b32 v0, v0, 56, v1
	s_waitcnt lgkmcnt(0)
	s_add_u32 s60, s3, s21
	v_ashrrev_i32_e32 v1, 31, v0
	v_lshl_add_u32 v129, v6, 4, 0
	s_addc_u32 s61, s90, 0
	v_lshlrev_b64 v[0:1], 1, v[0:1]
	v_readfirstlane_b32 s21, v129
	v_add_u32_e32 v9, 0x2000, v129
	v_lshl_add_u64 v[2:3], s[60:61], 0, v[0:1]
	s_mov_b32 m0, s21
	v_readfirstlane_b32 s21, v9
	v_add_u32_e32 v9, 0x4000, v129
	s_barrier
	global_load_lds_dwordx4 v[2:3], off
	v_lshl_add_u64 v[4:5], v[2:3], 0, s[10:11]
	s_mov_b32 m0, s21
	v_readfirstlane_b32 s21, v9
	global_load_lds_dwordx4 v[4:5], off
	v_lshl_add_u64 v[4:5], v[2:3], 0, s[12:13]
	s_mov_b32 m0, s21
	s_ashr_i32 s59, s58, 31
	global_load_lds_dwordx4 v[4:5], off
	v_add_u32_e32 v4, 0x6000, v129
	s_lshl_b64 s[88:89], s[58:59], 19
	v_readfirstlane_b32 s21, v4
	v_lshl_add_u64 v[2:3], v[2:3], 0, s[14:15]
	s_mov_b32 m0, s21
	s_add_u32 s88, s34, s88
	global_load_lds_dwordx4 v[2:3], off
	v_add_u32_e32 v2, 0x8000, v129
	s_addc_u32 s89, s35, s89
	v_readfirstlane_b32 s21, v2
	v_add_u32_e32 v4, 0xa000, v129
	v_lshl_add_u64 v[134:135], s[88:89], 0, v[0:1]
	s_mov_b32 m0, s21
	v_readfirstlane_b32 s21, v4
	v_add_u32_e32 v4, 0xc000, v129
	global_load_lds_dwordx4 v[134:135], off
	v_lshl_add_u64 v[2:3], v[134:135], 0, s[10:11]
	s_mov_b32 m0, s21
	v_readfirstlane_b32 s21, v4
	v_add_u32_e32 v4, 0xe000, v129
	global_load_lds_dwordx4 v[2:3], off
	v_lshl_add_u64 v[2:3], v[134:135], 0, s[12:13]
	s_mov_b32 m0, s21
	v_readfirstlane_b32 s21, v4
	global_load_lds_dwordx4 v[2:3], off
	v_lshl_add_u64 v[2:3], v[134:135], 0, s[14:15]
	s_mov_b32 m0, s21
	v_ashrrev_i32_e32 v4, 6, v6
	global_load_lds_dwordx4 v[2:3], off
	v_lshrrev_b32_e32 v5, 30, v4
	v_add_u32_e32 v5, v4, v5
	v_bfe_u32 v2, v6, 4, 2
	v_bfe_u32 v3, v6, 1, 3
	v_and_b32_e32 v6, 0x7fffc, v5
	v_sub_u32_e32 v4, v4, v6
	v_lshlrev_b32_e32 v139, 13, v4
	v_bitop3_b32 v4, v7, v3, 3 bitop3:0x6c
	v_bitop3_b32 v2, v2, v3, 4 bitop3:0x36
	s_add_u32 s60, s34, s20
	v_lshlrev_b32_e32 v5, 12, v5
	v_lshlrev_b32_e32 v4, 3, v4
	v_lshlrev_b32_e32 v2, 3, v2
	s_addc_u32 s61, s35, 0
	v_and_b32_e32 v138, 0xffffc000, v5
	v_lshl_add_u64 v[136:137], s[60:61], 0, v[0:1]
	s_mov_b64 s[60:61], 0
	v_lshlrev_b32_e32 v140, 1, v8
	v_lshlrev_b32_e32 v141, 1, v4
	v_lshlrev_b32_e32 v142, 1, v2
	s_mov_b32 s87, 0
	s_mov_b32 s59, 0
	v_mov_b32_e32 v8, v128
	v_mov_b32_e32 v9, v128
	v_mov_b32_e32 v10, v128
	v_mov_b32_e32 v11, v128
	v_mov_b32_e32 v20, v128
	v_mov_b32_e32 v21, v128
	v_mov_b32_e32 v22, v128
	v_mov_b32_e32 v23, v128
	v_mov_b32_e32 v0, v128
	v_mov_b32_e32 v1, v128
	v_mov_b32_e32 v2, v128
	v_mov_b32_e32 v3, v128
	v_mov_b32_e32 v4, v128
	v_mov_b32_e32 v5, v128
	v_mov_b32_e32 v6, v128
	v_mov_b32_e32 v7, v128
	v_mov_b32_e32 v12, v128
	v_mov_b32_e32 v13, v128
	v_mov_b32_e32 v14, v128
	v_mov_b32_e32 v15, v128
	v_mov_b32_e32 v24, v128
	v_mov_b32_e32 v25, v128
	v_mov_b32_e32 v26, v128
	v_mov_b32_e32 v27, v128
	v_mov_b32_e32 v16, v128
	v_mov_b32_e32 v17, v128
	v_mov_b32_e32 v18, v128
	v_mov_b32_e32 v19, v128
	v_mov_b32_e32 v28, v128
	v_mov_b32_e32 v29, v128
	v_mov_b32_e32 v30, v128
	v_mov_b32_e32 v31, v128
	v_mov_b32_e32 v32, v128
	v_mov_b32_e32 v33, v128
	v_mov_b32_e32 v34, v128
	v_mov_b32_e32 v35, v128
	v_mov_b32_e32 v40, v128
	v_mov_b32_e32 v41, v128
	v_mov_b32_e32 v42, v128
	v_mov_b32_e32 v43, v128
	v_mov_b32_e32 v36, v128
	v_mov_b32_e32 v37, v128
	v_mov_b32_e32 v38, v128
	v_mov_b32_e32 v39, v128
	v_mov_b32_e32 v44, v128
	v_mov_b32_e32 v45, v128
	v_mov_b32_e32 v46, v128
	v_mov_b32_e32 v47, v128
	v_mov_b32_e32 v48, v128
	v_mov_b32_e32 v49, v128
	v_mov_b32_e32 v50, v128
	v_mov_b32_e32 v51, v128
	v_mov_b32_e32 v56, v128
	v_mov_b32_e32 v57, v128
	v_mov_b32_e32 v58, v128
	v_mov_b32_e32 v59, v128
	v_mov_b32_e32 v52, v128
	v_mov_b32_e32 v53, v128
	v_mov_b32_e32 v54, v128
	v_mov_b32_e32 v55, v128
	v_mov_b32_e32 v60, v128
	v_mov_b32_e32 v61, v128
	v_mov_b32_e32 v62, v128
	v_mov_b32_e32 v63, v128
	v_mov_b32_e32 v64, v128
	v_mov_b32_e32 v65, v128
	v_mov_b32_e32 v66, v128
	v_mov_b32_e32 v67, v128
	v_mov_b32_e32 v72, v128
	v_mov_b32_e32 v73, v128
	v_mov_b32_e32 v74, v128
	v_mov_b32_e32 v75, v128
	v_mov_b32_e32 v68, v128
	v_mov_b32_e32 v69, v128
	v_mov_b32_e32 v70, v128
	v_mov_b32_e32 v71, v128
	v_mov_b32_e32 v76, v128
	v_mov_b32_e32 v77, v128
	v_mov_b32_e32 v78, v128
	v_mov_b32_e32 v79, v128
	v_mov_b32_e32 v80, v128
	v_mov_b32_e32 v81, v128
	v_mov_b32_e32 v82, v128
	v_mov_b32_e32 v83, v128
	v_mov_b32_e32 v88, v128
	v_mov_b32_e32 v89, v128
	v_mov_b32_e32 v90, v128
	v_mov_b32_e32 v91, v128
	v_mov_b32_e32 v84, v128
	v_mov_b32_e32 v85, v128
	v_mov_b32_e32 v86, v128
	v_mov_b32_e32 v87, v128
	v_mov_b32_e32 v92, v128
	v_mov_b32_e32 v93, v128
	v_mov_b32_e32 v94, v128
	v_mov_b32_e32 v95, v128
	v_mov_b32_e32 v96, v128
	v_mov_b32_e32 v97, v128
	v_mov_b32_e32 v98, v128
	v_mov_b32_e32 v99, v128
	v_mov_b32_e32 v104, v128
	v_mov_b32_e32 v105, v128
	v_mov_b32_e32 v106, v128
	v_mov_b32_e32 v107, v128
	v_mov_b32_e32 v100, v128
	v_mov_b32_e32 v101, v128
	v_mov_b32_e32 v102, v128
	v_mov_b32_e32 v103, v128
	v_mov_b32_e32 v108, v128
	v_mov_b32_e32 v109, v128
	v_mov_b32_e32 v110, v128
	v_mov_b32_e32 v111, v128
	v_mov_b32_e32 v112, v128
	v_mov_b32_e32 v113, v128
	v_mov_b32_e32 v114, v128
	v_mov_b32_e32 v115, v128
	v_mov_b32_e32 v120, v128
	v_mov_b32_e32 v121, v128
	v_mov_b32_e32 v122, v128
	v_mov_b32_e32 v123, v128
	v_mov_b32_e32 v116, v128
	v_mov_b32_e32 v117, v128
	v_mov_b32_e32 v118, v128
	v_mov_b32_e32 v119, v128
	v_mov_b32_e32 v124, v128
	v_mov_b32_e32 v125, v128
	v_mov_b32_e32 v126, v128
	v_mov_b32_e32 v127, v128
	s_waitcnt vmcnt(0) lgkmcnt(0)
	s_barrier
	v_add3_u32 v143, v138, v140, v141
	v_add3_u32 v180, v139, v140, v141
	v_add3_u32 v155, v138, v140, v142
	v_add3_u32 v222, v139, v140, v142
	v_readfirstlane_b32 s87, v129
	ds_read_b128 v[156:159], v143
	ds_read_b128 v[160:163], v143 offset:2048
	ds_read_b128 v[164:167], v143 offset:4096
	ds_read_b128 v[168:171], v143 offset:6144
	ds_read_b128 v[190:193], v180 offset:32768
	ds_read_b128 v[194:197], v180 offset:34816
	ds_read_b128 v[198:201], v180 offset:36864
	ds_read_b128 v[202:205], v180 offset:38912
	s_mov_b32 s59, 0
	s_mov_b64 s[60:61], 0
	s_add_u32 s87, s87, 0x10000
	s_add_u32 s88, s60, s16
	s_addc_u32 s89, s61, s17
	s_mov_b32 m0, s87
	v_lshl_add_u64 v[144:145], v[136:137], 0, s[88:89]
	global_load_lds_dwordx4 v[144:145], off sc1
	s_add_u32 s88, s60, s18
	s_addc_u32 s89, s61, s19
	s_add_u32 m0, s87, 0x2000
	v_lshl_add_u64 v[144:145], v[136:137], 0, s[88:89]
	global_load_lds_dwordx4 v[144:145], off sc1
	s_add_u32 s88, s60, s22
	s_addc_u32 s89, s61, s23
	s_add_u32 m0, s87, 0x4000
	v_lshl_add_u64 v[144:145], v[136:137], 0, s[88:89]
	global_load_lds_dwordx4 v[144:145], off sc1
	s_add_u32 s88, s60, s40
	s_addc_u32 s89, s61, s41
	s_add_u32 m0, s87, 0x6000
	v_lshl_add_u64 v[144:145], v[136:137], 0, s[88:89]
	global_load_lds_dwordx4 v[144:145], off sc1
	s_add_u32 s88, s60, s42
	s_addc_u32 s89, s61, s43
	s_add_u32 m0, s87, 0x8000
	v_lshl_add_u64 v[144:145], v[134:135], 0, s[88:89]
	global_load_lds_dwordx4 v[144:145], off sc1
	s_add_u32 s88, s60, s52
	s_addc_u32 s89, s61, s53
	s_add_u32 m0, s87, 0xa000
	v_lshl_add_u64 v[144:145], v[134:135], 0, s[88:89]
	global_load_lds_dwordx4 v[144:145], off sc1
	s_add_u32 s88, s60, s54
	s_addc_u32 s89, s61, s55
	s_add_u32 m0, s87, 0xc000
	v_lshl_add_u64 v[144:145], v[134:135], 0, s[88:89]
	global_load_lds_dwordx4 v[144:145], off sc1
	s_add_u32 s88, s60, s56
	s_addc_u32 s89, s61, s57
	s_add_u32 m0, s87, 0xe000
	v_lshl_add_u64 v[144:145], v[134:135], 0, s[88:89]
	global_load_lds_dwordx4 v[144:145], off sc1
	s_branch .Lg0_entry
.Lg0_top:
	s_waitcnt lgkmcnt(0)
	s_waitcnt vmcnt(0)
	s_barrier
	v_xor_b32_e32 v143, 0x10000, v143
	v_xor_b32_e32 v180, 0x10000, v180
	v_xor_b32_e32 v155, 0x10000, v155
	v_xor_b32_e32 v222, 0x10000, v222
	s_xor_b32 s87, s87, 0x10000
	ds_read_b128 v[156:159], v143
	ds_read_b128 v[160:163], v143 offset:2048
	ds_read_b128 v[164:167], v143 offset:4096
	ds_read_b128 v[168:171], v143 offset:6144
	ds_read_b128 v[190:193], v180 offset:32768
	ds_read_b128 v[194:197], v180 offset:34816
	ds_read_b128 v[198:201], v180 offset:36864
	ds_read_b128 v[202:205], v180 offset:38912
	v_mfma_f32_16x16x32_bf16 v[60:63], v[172:175], v[206:209], v[60:63]
	v_mfma_f32_16x16x32_bf16 v[52:55], v[172:175], v[210:213], v[52:55]
	s_add_u32 s88, s60, s16
	s_addc_u32 s89, s61, s17
	s_mov_b32 m0, s87
	v_lshl_add_u64 v[144:145], v[136:137], 0, s[88:89]
	global_load_lds_dwordx4 v[144:145], off sc1
	v_mfma_f32_16x16x32_bf16 v[56:59], v[172:175], v[214:217], v[56:59]
	v_mfma_f32_16x16x32_bf16 v[48:51], v[172:175], v[218:221], v[48:51]
	s_add_u32 s88, s60, s18
	s_addc_u32 s89, s61, s19
	s_add_u32 m0, s87, 0x2000
	v_lshl_add_u64 v[144:145], v[136:137], 0, s[88:89]
	global_load_lds_dwordx4 v[144:145], off sc1
	v_mfma_f32_16x16x32_bf16 v[44:47], v[176:179], v[206:209], v[44:47]
	v_mfma_f32_16x16x32_bf16 v[36:39], v[176:179], v[210:213], v[36:39]
	s_add_u32 s88, s60, s22
	s_addc_u32 s89, s61, s23
	s_add_u32 m0, s87, 0x4000
	v_lshl_add_u64 v[144:145], v[136:137], 0, s[88:89]
	global_load_lds_dwordx4 v[144:145], off sc1
	v_mfma_f32_16x16x32_bf16 v[40:43], v[176:179], v[214:217], v[40:43]
	v_mfma_f32_16x16x32_bf16 v[32:35], v[176:179], v[218:221], v[32:35]
	s_add_u32 s88, s60, s40
	s_addc_u32 s89, s61, s41
	s_add_u32 m0, s87, 0x6000
	v_lshl_add_u64 v[144:145], v[136:137], 0, s[88:89]
	global_load_lds_dwordx4 v[144:145], off sc1
	v_mfma_f32_16x16x32_bf16 v[28:31], v[182:185], v[206:209], v[28:31]
	v_mfma_f32_16x16x32_bf16 v[16:19], v[182:185], v[210:213], v[16:19]
	s_add_u32 s88, s60, s42
	s_addc_u32 s89, s61, s43
	s_add_u32 m0, s87, 0x8000
	v_lshl_add_u64 v[144:145], v[134:135], 0, s[88:89]
	global_load_lds_dwordx4 v[144:145], off sc1
	v_mfma_f32_16x16x32_bf16 v[24:27], v[182:185], v[214:217], v[24:27]
	v_mfma_f32_16x16x32_bf16 v[12:15], v[182:185], v[218:221], v[12:15]
	s_add_u32 s88, s60, s52
	s_addc_u32 s89, s61, s53
	s_add_u32 m0, s87, 0xa000
	v_lshl_add_u64 v[144:145], v[134:135], 0, s[88:89]
	global_load_lds_dwordx4 v[144:145], off sc1
	v_mfma_f32_16x16x32_bf16 v[4:7], v[186:189], v[206:209], v[4:7]
	v_mfma_f32_16x16x32_bf16 v[0:3], v[186:189], v[210:213], v[0:3]
	s_add_u32 s88, s60, s54
	s_addc_u32 s89, s61, s55
	s_add_u32 m0, s87, 0xc000
	v_lshl_add_u64 v[144:145], v[134:135], 0, s[88:89]
	global_load_lds_dwordx4 v[144:145], off sc1
	v_mfma_f32_16x16x32_bf16 v[20:23], v[186:189], v[214:217], v[20:23]
	v_mfma_f32_16x16x32_bf16 v[8:11], v[186:189], v[218:221], v[8:11]
	s_add_u32 s88, s60, s56
	s_addc_u32 s89, s61, s57
	s_add_u32 m0, s87, 0xe000
	v_lshl_add_u64 v[144:145], v[134:135], 0, s[88:89]
	global_load_lds_dwordx4 v[144:145], off sc1

.LBB0_263:
	s_ashr_i32 s21, s58, 2
	v_mov_b32_e32 v6, v181
	s_and_b32 s6, s58, 7
	s_and_b32 s21, s21, -8
	s_or_b32 s48, s21, s6
	v_lshrrev_b32_e32 v7, 4, v6
	v_lshlrev_b32_e32 v1, 6, v6
	v_xor_b32_e32 v0, v7, v6
	v_and_b32_e32 v8, 0x3c0, v1
	v_lshlrev_b32_e32 v1, 8, v6
	s_ashr_i32 s49, s48, 31
	v_lshlrev_b32_e32 v0, 3, v0
	v_and_b32_e32 v1, 0xfffff800, v1
	s_and_b32 s20, s57, 7
	s_bfe_u32 s6, s58, 0x20003
	s_lshl_b64 s[50:51], s[48:49], 20
	v_and_or_b32 v0, v0, 56, v1
	s_add_u32 s50, s3, s50
	v_ashrrev_i32_e32 v1, 31, v0
	s_addc_u32 s51, s54, s51
	v_lshlrev_b64 v[0:1], 1, v[0:1]
	v_lshl_add_u32 v135, v6, 4, 0
	v_lshl_add_u64 v[2:3], s[50:51], 0, v[0:1]
	v_readfirstlane_b32 s50, v135
	v_add_u32_e32 v9, 0x2000, v135
	s_mov_b32 m0, s50
	v_readfirstlane_b32 s50, v9
	v_add_u32_e32 v9, 0x4000, v135
	s_waitcnt lgkmcnt(0)
	s_barrier
	global_load_lds_dwordx4 v[2:3], off
	v_lshl_add_u64 v[4:5], v[2:3], 0, s[8:9]
	s_mov_b32 m0, s50
	v_readfirstlane_b32 s50, v9
	global_load_lds_dwordx4 v[4:5], off
	v_lshl_add_u64 v[4:5], v[2:3], 0, s[10:11]
	s_mov_b32 m0, s50
	s_lshl_b32 s49, s6, 20
	global_load_lds_dwordx4 v[4:5], off
	v_add_u32_e32 v4, 0x6000, v135
	s_add_u32 s52, s55, s49
	v_readfirstlane_b32 s50, v4
	v_add_u32_e32 v4, 0x8000, v135
	s_addc_u32 s53, s56, 0
	v_lshl_add_u64 v[2:3], v[2:3], 0, s[12:13]
	s_mov_b32 m0, s50
	v_readfirstlane_b32 s50, v4
	v_add_u32_e32 v9, 0xa000, v135
	global_load_lds_dwordx4 v[2:3], off
	v_lshl_add_u64 v[2:3], s[52:53], 0, v[0:1]
	s_mov_b32 m0, s50
	v_readfirstlane_b32 s50, v9
	v_add_u32_e32 v9, 0xc000, v135
	global_load_lds_dwordx4 v[2:3], off
	v_lshl_add_u64 v[4:5], v[2:3], 0, s[8:9]
	s_mov_b32 m0, s50
	v_readfirstlane_b32 s50, v9
	global_load_lds_dwordx4 v[4:5], off
	v_lshl_add_u64 v[4:5], v[2:3], 0, s[10:11]
	s_mov_b32 m0, s50
	v_lshl_add_u64 v[2:3], v[2:3], 0, s[12:13]
	global_load_lds_dwordx4 v[4:5], off
	v_add_u32_e32 v4, 0xe000, v135
	v_mov_b32_e32 v12, 0
	v_readfirstlane_b32 s50, v4
	s_mov_b32 m0, s50
	v_ashrrev_i32_e32 v4, 6, v6
	global_load_lds_dwordx4 v[2:3], off
	s_or_b32 s50, s21, s20
	v_lshrrev_b32_e32 v5, 30, v4
	s_ashr_i32 s51, s50, 31
	v_add_u32_e32 v5, v4, v5
	s_lshl_b64 s[50:51], s[50:51], 20
	v_bfe_u32 v2, v6, 4, 2
	v_bfe_u32 v3, v6, 1, 3
	v_and_b32_e32 v6, 0x7fffc, v5
	s_add_u32 s50, s34, s50
	v_sub_u32_e32 v4, v4, v6
	s_addc_u32 s51, s35, s51
	v_lshlrev_b32_e32 v137, 13, v4
	v_bitop3_b32 v4, v7, v3, 3 bitop3:0x6c
	v_bitop3_b32 v2, v2, v3, 4 bitop3:0x36
	v_lshl_add_u64 v[130:131], s[50:51], 0, v[0:1]
	s_add_u32 s50, s34, s49
	v_lshlrev_b32_e32 v5, 12, v5
	v_lshlrev_b32_e32 v4, 3, v4
	v_lshlrev_b32_e32 v2, 3, v2
	s_addc_u32 s51, s35, 0
	v_and_b32_e32 v136, 0xffffc000, v5
	v_lshl_add_u64 v[132:133], s[50:51], 0, v[0:1]
	s_mov_b64 s[50:51], 0
	v_lshlrev_b32_e32 v138, 1, v8
	v_lshlrev_b32_e32 v139, 1, v4
	v_lshlrev_b32_e32 v140, 1, v2
	s_mov_b32 s59, 0
	s_mov_b32 s49, 0
	v_mov_b32_e32 v13, v12
	v_mov_b32_e32 v14, v12
	v_mov_b32_e32 v15, v12
	v_mov_b32_e32 v24, v12
	v_mov_b32_e32 v25, v12
	v_mov_b32_e32 v26, v12
	v_mov_b32_e32 v27, v12
	v_mov_b32_e32 v0, v12
	v_mov_b32_e32 v1, v12
	v_mov_b32_e32 v2, v12
	v_mov_b32_e32 v3, v12
	v_mov_b32_e32 v4, v12
	v_mov_b32_e32 v5, v12
	v_mov_b32_e32 v6, v12
	v_mov_b32_e32 v7, v12
	v_mov_b32_e32 v8, v12
	v_mov_b32_e32 v9, v12
	v_mov_b32_e32 v10, v12
	v_mov_b32_e32 v11, v12
	v_mov_b32_e32 v16, v12
	v_mov_b32_e32 v17, v12
	v_mov_b32_e32 v18, v12
	v_mov_b32_e32 v19, v12
	v_mov_b32_e32 v20, v12
	v_mov_b32_e32 v21, v12
	v_mov_b32_e32 v22, v12
	v_mov_b32_e32 v23, v12
	v_mov_b32_e32 v28, v12
	v_mov_b32_e32 v29, v12
	v_mov_b32_e32 v30, v12
	v_mov_b32_e32 v31, v12
	v_mov_b32_e32 v32, v12
	v_mov_b32_e32 v33, v12
	v_mov_b32_e32 v34, v12
	v_mov_b32_e32 v35, v12
	v_mov_b32_e32 v36, v12
	v_mov_b32_e32 v37, v12
	v_mov_b32_e32 v38, v12
	v_mov_b32_e32 v39, v12
	v_mov_b32_e32 v40, v12
	v_mov_b32_e32 v41, v12
	v_mov_b32_e32 v42, v12
	v_mov_b32_e32 v43, v12
	v_mov_b32_e32 v44, v12
	v_mov_b32_e32 v45, v12
	v_mov_b32_e32 v46, v12
	v_mov_b32_e32 v47, v12
	v_mov_b32_e32 v48, v12
	v_mov_b32_e32 v49, v12
	v_mov_b32_e32 v50, v12
	v_mov_b32_e32 v51, v12
	v_mov_b32_e32 v52, v12
	v_mov_b32_e32 v53, v12
	v_mov_b32_e32 v54, v12
	v_mov_b32_e32 v55, v12
	v_mov_b32_e32 v56, v12
	v_mov_b32_e32 v57, v12
	v_mov_b32_e32 v58, v12
	v_mov_b32_e32 v59, v12
	v_mov_b32_e32 v60, v12
	v_mov_b32_e32 v61, v12
	v_mov_b32_e32 v62, v12
	v_mov_b32_e32 v63, v12
	v_mov_b32_e32 v64, v12
	v_mov_b32_e32 v65, v12
	v_mov_b32_e32 v66, v12
	v_mov_b32_e32 v67, v12
	v_mov_b32_e32 v68, v12
	v_mov_b32_e32 v69, v12
	v_mov_b32_e32 v70, v12
	v_mov_b32_e32 v71, v12
	v_mov_b32_e32 v72, v12
	v_mov_b32_e32 v73, v12
	v_mov_b32_e32 v74, v12
	v_mov_b32_e32 v75, v12
	v_mov_b32_e32 v76, v12
	v_mov_b32_e32 v77, v12
	v_mov_b32_e32 v78, v12
	v_mov_b32_e32 v79, v12
	v_mov_b32_e32 v80, v12
	v_mov_b32_e32 v81, v12
	v_mov_b32_e32 v82, v12
	v_mov_b32_e32 v83, v12
	v_mov_b32_e32 v84, v12
	v_mov_b32_e32 v85, v12
	v_mov_b32_e32 v86, v12
	v_mov_b32_e32 v87, v12
	v_mov_b32_e32 v88, v12
	v_mov_b32_e32 v89, v12
	v_mov_b32_e32 v90, v12
	v_mov_b32_e32 v91, v12
	v_mov_b32_e32 v92, v12
	v_mov_b32_e32 v93, v12
	v_mov_b32_e32 v94, v12
	v_mov_b32_e32 v95, v12
	v_mov_b32_e32 v96, v12
	v_mov_b32_e32 v97, v12
	v_mov_b32_e32 v98, v12
	v_mov_b32_e32 v99, v12
	v_mov_b32_e32 v100, v12
	v_mov_b32_e32 v101, v12
	v_mov_b32_e32 v102, v12
	v_mov_b32_e32 v103, v12
	v_mov_b32_e32 v104, v12
	v_mov_b32_e32 v105, v12
	v_mov_b32_e32 v106, v12
	v_mov_b32_e32 v107, v12
	v_mov_b32_e32 v108, v12
	v_mov_b32_e32 v109, v12
	v_mov_b32_e32 v110, v12
	v_mov_b32_e32 v111, v12
	v_mov_b32_e32 v112, v12
	v_mov_b32_e32 v113, v12
	v_mov_b32_e32 v114, v12
	v_mov_b32_e32 v115, v12
	v_mov_b32_e32 v116, v12
	v_mov_b32_e32 v117, v12
	v_mov_b32_e32 v118, v12
	v_mov_b32_e32 v119, v12
	v_mov_b32_e32 v120, v12
	v_mov_b32_e32 v121, v12
	v_mov_b32_e32 v122, v12
	v_mov_b32_e32 v123, v12
	v_mov_b32_e32 v124, v12
	v_mov_b32_e32 v125, v12
	v_mov_b32_e32 v126, v12
	v_mov_b32_e32 v127, v12
	s_waitcnt vmcnt(0) lgkmcnt(0)
	s_barrier
	v_add3_u32 v141, v136, v138, v139
	v_add3_u32 v210, v137, v138, v139
	v_add3_u32 v180, v136, v138, v140
	v_add3_u32 v211, v137, v138, v140
	v_readfirstlane_b32 s59, v135
	ds_read_b128 v[142:145], v141
	ds_read_b128 v[146:149], v141 offset:2048
	ds_read_b128 v[150:153], v141 offset:4096
	ds_read_b128 v[154:157], v141 offset:6144
	ds_read_b128 v[174:177], v210 offset:32768
	ds_read_b128 v[182:185], v210 offset:34816
	ds_read_b128 v[186:189], v210 offset:36864
	ds_read_b128 v[190:193], v210 offset:38912
	s_mov_b32 s49, 0
	s_mov_b64 s[50:51], 0
	s_add_u32 s59, s59, 0x10000
	s_add_u32 s52, s50, s14
	s_addc_u32 s53, s51, s15
	s_mov_b32 m0, s59
	v_lshl_add_u64 v[178:179], v[130:131], 0, s[52:53]
	global_load_lds_dwordx4 v[178:179], off sc1
	s_add_u32 s52, s50, s16
	s_addc_u32 s53, s51, s17
	s_add_u32 m0, s59, 0x2000
	v_lshl_add_u64 v[178:179], v[130:131], 0, s[52:53]
	global_load_lds_dwordx4 v[178:179], off sc1
	s_add_u32 s52, s50, s18
	s_addc_u32 s53, s51, s19
	s_add_u32 m0, s59, 0x4000
	v_lshl_add_u64 v[178:179], v[130:131], 0, s[52:53]
	global_load_lds_dwordx4 v[178:179], off sc1
	s_add_u32 s52, s50, s22
	s_addc_u32 s53, s51, s23
	s_add_u32 m0, s59, 0x6000
	v_lshl_add_u64 v[178:179], v[130:131], 0, s[52:53]
	global_load_lds_dwordx4 v[178:179], off sc1
	s_add_u32 s52, s50, s40
	s_addc_u32 s53, s51, s41
	s_add_u32 m0, s59, 0x8000
	v_lshl_add_u64 v[178:179], v[132:133], 0, s[52:53]
	global_load_lds_dwordx4 v[178:179], off sc1
	s_add_u32 s52, s50, s42
	s_addc_u32 s53, s51, s43
	s_add_u32 m0, s59, 0xa000
	v_lshl_add_u64 v[178:179], v[132:133], 0, s[52:53]
	global_load_lds_dwordx4 v[178:179], off sc1
	s_add_u32 s52, s50, s44
	s_addc_u32 s53, s51, s45
	s_add_u32 m0, s59, 0xc000
	v_lshl_add_u64 v[178:179], v[132:133], 0, s[52:53]
	global_load_lds_dwordx4 v[178:179], off sc1
	s_add_u32 s52, s50, s46
	s_addc_u32 s53, s51, s47
	s_add_u32 m0, s59, 0xe000
	v_lshl_add_u64 v[178:179], v[132:133], 0, s[52:53]
	global_load_lds_dwordx4 v[178:179], off sc1
	s_branch .Lg1_entry
.Lg1_top:
	s_waitcnt lgkmcnt(0)
	s_waitcnt vmcnt(0)
	s_barrier
	v_xor_b32_e32 v141, 0x10000, v141
	v_xor_b32_e32 v210, 0x10000, v210
	v_xor_b32_e32 v180, 0x10000, v180
	v_xor_b32_e32 v211, 0x10000, v211
	s_xor_b32 s59, s59, 0x10000
	ds_read_b128 v[142:145], v141
	ds_read_b128 v[146:149], v141 offset:2048
	ds_read_b128 v[150:153], v141 offset:4096
	ds_read_b128 v[154:157], v141 offset:6144
	ds_read_b128 v[174:177], v210 offset:32768
	ds_read_b128 v[182:185], v210 offset:34816
	ds_read_b128 v[186:189], v210 offset:36864
	ds_read_b128 v[190:193], v210 offset:38912
	v_mfma_f32_16x16x32_bf16 v[60:63], v[158:161], v[194:197], v[60:63]
	v_mfma_f32_16x16x32_bf16 v[56:59], v[158:161], v[198:201], v[56:59]
	s_add_u32 s52, s50, s14
	s_addc_u32 s53, s51, s15
	s_mov_b32 m0, s59
	v_lshl_add_u64 v[178:179], v[130:131], 0, s[52:53]
	global_load_lds_dwordx4 v[178:179], off sc1
	v_mfma_f32_16x16x32_bf16 v[52:55], v[158:161], v[202:205], v[52:55]
	v_mfma_f32_16x16x32_bf16 v[48:51], v[158:161], v[206:209], v[48:51]
	s_add_u32 s52, s50, s16
	s_addc_u32 s53, s51, s17
	s_add_u32 m0, s59, 0x2000
	v_lshl_add_u64 v[178:179], v[130:131], 0, s[52:53]
	global_load_lds_dwordx4 v[178:179], off sc1
	v_mfma_f32_16x16x32_bf16 v[44:47], v[162:165], v[194:197], v[44:47]
	v_mfma_f32_16x16x32_bf16 v[40:43], v[162:165], v[198:201], v[40:43]
	s_add_u32 s52, s50, s18
	s_addc_u32 s53, s51, s19
	s_add_u32 m0, s59, 0x4000
	v_lshl_add_u64 v[178:179], v[130:131], 0, s[52:53]
	global_load_lds_dwordx4 v[178:179], off sc1
	v_mfma_f32_16x16x32_bf16 v[36:39], v[162:165], v[202:205], v[36:39]
	v_mfma_f32_16x16x32_bf16 v[32:35], v[162:165], v[206:209], v[32:35]
	s_add_u32 s52, s50, s22
	s_addc_u32 s53, s51, s23
	s_add_u32 m0, s59, 0x6000
	v_lshl_add_u64 v[178:179], v[130:131], 0, s[52:53]
	global_load_lds_dwordx4 v[178:179], off sc1
	v_mfma_f32_16x16x32_bf16 v[28:31], v[166:169], v[194:197], v[28:31]
	v_mfma_f32_16x16x32_bf16 v[20:23], v[166:169], v[198:201], v[20:23]
	s_add_u32 s52, s50, s40
	s_addc_u32 s53, s51, s41
	s_add_u32 m0, s59, 0x8000
	v_lshl_add_u64 v[178:179], v[132:133], 0, s[52:53]
	global_load_lds_dwordx4 v[178:179], off sc1
	v_mfma_f32_16x16x32_bf16 v[16:19], v[166:169], v[202:205], v[16:19]
	v_mfma_f32_16x16x32_bf16 v[8:11], v[166:169], v[206:209], v[8:11]
	s_add_u32 s52, s50, s42
	s_addc_u32 s53, s51, s43
	s_add_u32 m0, s59, 0xa000
	v_lshl_add_u64 v[178:179], v[132:133], 0, s[52:53]
	global_load_lds_dwordx4 v[178:179], off sc1
	v_mfma_f32_16x16x32_bf16 v[4:7], v[170:173], v[194:197], v[4:7]
	v_mfma_f32_16x16x32_bf16 v[0:3], v[170:173], v[198:201], v[0:3]
	s_add_u32 s52, s50, s44
	s_addc_u32 s53, s51, s45
	s_add_u32 m0, s59, 0xc000
	v_lshl_add_u64 v[178:179], v[132:133], 0, s[52:53]
	global_load_lds_dwordx4 v[178:179], off sc1
	v_mfma_f32_16x16x32_bf16 v[24:27], v[170:173], v[202:205], v[24:27]
	v_mfma_f32_16x16x32_bf16 v[12:15], v[170:173], v[206:209], v[12:15]
	s_add_u32 s52, s50, s46
	s_addc_u32 s53, s51, s47
	s_add_u32 m0, s59, 0xe000
	v_lshl_add_u64 v[178:179], v[132:133], 0, s[52:53]
	global_load_lds_dwordx4 v[178:179], off sc1

.LBB0_452:
	s_ashr_i32 s46, s60, 3
	s_and_b32 s21, s60, 7
	s_and_b32 s62, s46, -8
	v_mov_b32_e32 v6, v181
	s_or_b32 s46, s62, s21
	s_ashr_i32 s47, s46, 31
	v_lshrrev_b32_e32 v7, 4, v6
	v_lshlrev_b32_e32 v1, 6, v6
	v_xor_b32_e32 v0, v7, v6
	v_and_b32_e32 v8, 0x3c0, v1
	v_lshlrev_b32_e32 v1, 7, v6
	s_and_b32 s20, s55, 7
	s_bfe_u32 s61, s60, 0x30003
	s_lshl_b64 s[48:49], s[46:47], 19
	v_lshlrev_b32_e32 v0, 3, v0
	v_and_b32_e32 v1, 0xfffffc00, v1
	s_add_u32 s48, s3, s48
	v_and_or_b32 v0, v0, 56, v1
	s_addc_u32 s49, s54, s49
	s_lshl_b32 s21, s61, 19
	v_ashrrev_i32_e32 v1, 31, v0
	v_lshl_add_u32 v140, v6, 4, 0
	s_add_u32 s50, s34, s21
	v_lshlrev_b64 v[0:1], 1, v[0:1]
	v_readfirstlane_b32 s21, v140
	v_add_u32_e32 v9, 0x2000, v140
	v_lshl_add_u64 v[2:3], s[48:49], 0, v[0:1]
	s_mov_b32 m0, s21
	v_readfirstlane_b32 s21, v9
	v_add_u32_e32 v9, 0x4000, v140
	s_barrier
	global_load_lds_dwordx4 v[2:3], off
	v_lshl_add_u64 v[4:5], v[2:3], 0, s[6:7]
	s_mov_b32 m0, s21
	v_readfirstlane_b32 s21, v9
	global_load_lds_dwordx4 v[4:5], off
	v_lshl_add_u64 v[4:5], v[2:3], 0, s[8:9]
	s_mov_b32 m0, s21
	v_lshl_add_u64 v[2:3], v[2:3], 0, s[10:11]
	global_load_lds_dwordx4 v[4:5], off
	v_add_u32_e32 v4, 0x6000, v140
	s_addc_u32 s51, s35, 0
	v_readfirstlane_b32 s21, v4
	s_mov_b32 m0, s21
	v_add_u32_e32 v4, 0xa000, v140
	global_load_lds_dwordx4 v[2:3], off
	v_add_u32_e32 v2, 0x8000, v140
	v_lshl_add_u64 v[132:133], s[50:51], 0, v[0:1]
	v_readfirstlane_b32 s21, v2
	s_mov_b32 m0, s21
	v_readfirstlane_b32 s21, v4
	v_add_u32_e32 v4, 0xc000, v140
	global_load_lds_dwordx4 v[132:133], off
	v_lshl_add_u64 v[2:3], v[132:133], 0, s[6:7]
	s_mov_b32 m0, s21
	v_readfirstlane_b32 s21, v4
	v_add_u32_e32 v4, 0xe000, v140
	global_load_lds_dwordx4 v[2:3], off
	v_lshl_add_u64 v[2:3], v[132:133], 0, s[8:9]
	s_mov_b32 m0, s21
	v_readfirstlane_b32 s21, v4
	global_load_lds_dwordx4 v[2:3], off
	v_lshl_add_u64 v[2:3], v[132:133], 0, s[10:11]
	s_mov_b32 m0, s21
	v_ashrrev_i32_e32 v4, 6, v6
	global_load_lds_dwordx4 v[2:3], off
	v_lshrrev_b32_e32 v5, 30, v4
	v_add_u32_e32 v5, v4, v5
	s_or_b32 s48, s62, s20
	v_bfe_u32 v2, v6, 4, 2
	v_bfe_u32 v3, v6, 1, 3
	v_and_b32_e32 v6, 0x7fffc, v5
	s_ashr_i32 s49, s48, 31
	v_sub_u32_e32 v4, v4, v6
	s_lshl_b64 s[48:49], s[48:49], 19
	v_lshlrev_b32_e32 v142, 13, v4
	v_bitop3_b32 v4, v7, v3, 3 bitop3:0x6c
	v_bitop3_b32 v2, v2, v3, 4 bitop3:0x36
	s_add_u32 s48, s34, s48
	v_lshlrev_b32_e32 v5, 12, v5
	v_lshlrev_b32_e32 v4, 3, v4
	v_lshlrev_b32_e32 v2, 3, v2
	s_addc_u32 s49, s35, s49
	v_and_b32_e32 v141, 0xffffc000, v5
	v_lshl_add_u64 v[134:135], s[48:49], 0, v[0:1]
	s_mov_b64 s[48:49], 0
	v_lshlrev_b32_e32 v143, 1, v8
	v_lshlrev_b32_e32 v144, 1, v4
	v_lshlrev_b32_e32 v145, 1, v2
	s_mov_b32 s62, 0
	s_mov_b32 s47, 0
	v_mov_b32_e32 v40, 0
	v_mov_b32_e32 v41, v129
	v_mov_b32_e32 v42, v129
	v_mov_b32_e32 v43, v129
	v_mov_b32_e32 v48, 0
	v_mov_b32_e32 v49, v129
	v_mov_b32_e32 v50, v129
	v_mov_b32_e32 v51, v129
	v_mov_b32_e32 v0, 0
	v_mov_b32_e32 v1, v129
	v_mov_b32_e32 v2, v129
	v_mov_b32_e32 v3, v129
	v_mov_b32_e32 v4, 0
	v_mov_b32_e32 v5, v129
	v_mov_b32_e32 v6, v129
	v_mov_b32_e32 v7, v129
	v_mov_b32_e32 v8, 0
	v_mov_b32_e32 v9, v129
	v_mov_b32_e32 v10, v129
	v_mov_b32_e32 v11, v129
	v_mov_b32_e32 v12, 0
	v_mov_b32_e32 v13, v129
	v_mov_b32_e32 v14, v129
	v_mov_b32_e32 v15, v129
	v_mov_b32_e32 v16, 0
	v_mov_b32_e32 v17, v129
	v_mov_b32_e32 v18, v129
	v_mov_b32_e32 v19, v129
	v_mov_b32_e32 v20, 0
	v_mov_b32_e32 v21, v129
	v_mov_b32_e32 v22, v129
	v_mov_b32_e32 v23, v129
	v_mov_b32_e32 v24, 0
	v_mov_b32_e32 v25, v129
	v_mov_b32_e32 v26, v129
	v_mov_b32_e32 v27, v129
	v_mov_b32_e32 v28, 0
	v_mov_b32_e32 v29, v129
	v_mov_b32_e32 v30, v129
	v_mov_b32_e32 v31, v129
	v_mov_b32_e32 v32, 0
	v_mov_b32_e32 v33, v129
	v_mov_b32_e32 v34, v129
	v_mov_b32_e32 v35, v129
	v_mov_b32_e32 v36, 0
	v_mov_b32_e32 v37, v129
	v_mov_b32_e32 v38, v129
	v_mov_b32_e32 v39, v129
	v_mov_b32_e32 v44, 0
	v_mov_b32_e32 v45, v129
	v_mov_b32_e32 v46, v129
	v_mov_b32_e32 v47, v129
	v_mov_b32_e32 v52, 0
	v_mov_b32_e32 v53, v129
	v_mov_b32_e32 v54, v129
	v_mov_b32_e32 v55, v129
	v_mov_b32_e32 v56, 0
	v_mov_b32_e32 v57, v129
	v_mov_b32_e32 v58, v129
	v_mov_b32_e32 v59, v129
	v_mov_b32_e32 v60, 0
	v_mov_b32_e32 v61, v129
	v_mov_b32_e32 v62, v129
	v_mov_b32_e32 v63, v129
	v_mov_b32_e32 v64, 0
	v_mov_b32_e32 v65, v129
	v_mov_b32_e32 v66, v129
	v_mov_b32_e32 v67, v129
	v_mov_b32_e32 v68, 0
	v_mov_b32_e32 v69, v129
	v_mov_b32_e32 v70, v129
	v_mov_b32_e32 v71, v129
	v_mov_b32_e32 v72, 0
	v_mov_b32_e32 v73, v129
	v_mov_b32_e32 v74, v129
	v_mov_b32_e32 v75, v129
	v_mov_b32_e32 v76, 0
	v_mov_b32_e32 v77, v129
	v_mov_b32_e32 v78, v129
	v_mov_b32_e32 v79, v129
	v_mov_b32_e32 v80, 0
	v_mov_b32_e32 v81, v129
	v_mov_b32_e32 v82, v129
	v_mov_b32_e32 v83, v129
	v_mov_b32_e32 v84, 0
	v_mov_b32_e32 v85, v129
	v_mov_b32_e32 v86, v129
	v_mov_b32_e32 v87, v129
	v_mov_b32_e32 v88, 0
	v_mov_b32_e32 v89, v129
	v_mov_b32_e32 v90, v129
	v_mov_b32_e32 v91, v129
	v_mov_b32_e32 v92, 0
	v_mov_b32_e32 v93, v129
	v_mov_b32_e32 v94, v129
	v_mov_b32_e32 v95, v129
	v_mov_b32_e32 v96, 0
	v_mov_b32_e32 v97, v129
	v_mov_b32_e32 v98, v129
	v_mov_b32_e32 v99, v129
	v_mov_b32_e32 v100, 0
	v_mov_b32_e32 v101, v129
	v_mov_b32_e32 v102, v129
	v_mov_b32_e32 v103, v129
	v_mov_b32_e32 v104, 0
	v_mov_b32_e32 v105, v129
	v_mov_b32_e32 v106, v129
	v_mov_b32_e32 v107, v129
	v_mov_b32_e32 v108, 0
	v_mov_b32_e32 v109, v129
	v_mov_b32_e32 v110, v129
	v_mov_b32_e32 v111, v129
	v_mov_b32_e32 v112, 0
	v_mov_b32_e32 v113, v129
	v_mov_b32_e32 v114, v129
	v_mov_b32_e32 v115, v129
	v_mov_b32_e32 v116, 0
	v_mov_b32_e32 v117, v129
	v_mov_b32_e32 v118, v129
	v_mov_b32_e32 v119, v129
	v_mov_b32_e32 v120, 0
	v_mov_b32_e32 v121, v129
	v_mov_b32_e32 v122, v129
	v_mov_b32_e32 v123, v129
	v_mov_b32_e32 v124, 0
	v_mov_b32_e32 v125, v129
	v_mov_b32_e32 v126, v129
	v_mov_b32_e32 v127, v129
	s_waitcnt vmcnt(0) lgkmcnt(0)
	s_barrier
	v_add3_u32 v180, v141, v143, v144
	v_add3_u32 v215, v142, v143, v144
	v_add3_u32 v214, v141, v143, v145
	v_add3_u32 v216, v142, v143, v145
	v_readfirstlane_b32 s62, v140
	ds_read_b128 v[146:149], v180
	ds_read_b128 v[150:153], v180 offset:2048
	ds_read_b128 v[154:157], v180 offset:4096
	ds_read_b128 v[158:161], v180 offset:6144
	ds_read_b128 v[182:185], v215 offset:32768
	ds_read_b128 v[186:189], v215 offset:34816
	ds_read_b128 v[190:193], v215 offset:36864
	ds_read_b128 v[194:197], v215 offset:38912
	s_mov_b32 s47, 0
	s_mov_b64 s[48:49], 0
	s_add_u32 s62, s62, 0x10000
	s_add_u32 s50, s48, s12
	s_addc_u32 s51, s49, s13
	s_mov_b32 m0, s62
	v_lshl_add_u64 v[178:179], v[134:135], 0, s[50:51]
	global_load_lds_dwordx4 v[178:179], off sc1
	s_add_u32 s50, s48, s14
	s_addc_u32 s51, s49, s15
	s_add_u32 m0, s62, 0x2000
	v_lshl_add_u64 v[178:179], v[134:135], 0, s[50:51]
	global_load_lds_dwordx4 v[178:179], off sc1
	s_add_u32 s50, s48, s16
	s_addc_u32 s51, s49, s17
	s_add_u32 m0, s62, 0x4000
	v_lshl_add_u64 v[178:179], v[134:135], 0, s[50:51]
	global_load_lds_dwordx4 v[178:179], off sc1
	s_add_u32 s50, s48, s18
	s_addc_u32 s51, s49, s19
	s_add_u32 m0, s62, 0x6000
	v_lshl_add_u64 v[178:179], v[134:135], 0, s[50:51]
	global_load_lds_dwordx4 v[178:179], off sc1
	s_add_u32 s50, s48, s22
	s_addc_u32 s51, s49, s23
	s_add_u32 m0, s62, 0x8000
	v_lshl_add_u64 v[178:179], v[132:133], 0, s[50:51]
	global_load_lds_dwordx4 v[178:179], off sc1
	s_add_u32 s50, s48, s36
	s_addc_u32 s51, s49, s37
	s_add_u32 m0, s62, 0xa000
	v_lshl_add_u64 v[178:179], v[132:133], 0, s[50:51]
	global_load_lds_dwordx4 v[178:179], off sc1
	s_add_u32 s50, s48, s40
	s_addc_u32 s51, s49, s41
	s_add_u32 m0, s62, 0xc000
	v_lshl_add_u64 v[178:179], v[132:133], 0, s[50:51]
	global_load_lds_dwordx4 v[178:179], off sc1
	s_add_u32 s50, s48, s42
	s_addc_u32 s51, s49, s43
	s_add_u32 m0, s62, 0xe000
	v_lshl_add_u64 v[178:179], v[132:133], 0, s[50:51]
	global_load_lds_dwordx4 v[178:179], off sc1
	s_branch .Lg2_entry
.Lg2_top:
	s_waitcnt lgkmcnt(0)
	s_waitcnt vmcnt(0)
	s_barrier
	v_xor_b32_e32 v180, 0x10000, v180
	v_xor_b32_e32 v215, 0x10000, v215
	v_xor_b32_e32 v214, 0x10000, v214
	v_xor_b32_e32 v216, 0x10000, v216
	s_xor_b32 s62, s62, 0x10000
	ds_read_b128 v[146:149], v180
	ds_read_b128 v[150:153], v180 offset:2048
	ds_read_b128 v[154:157], v180 offset:4096
	ds_read_b128 v[158:161], v180 offset:6144
	ds_read_b128 v[182:185], v215 offset:32768
	ds_read_b128 v[186:189], v215 offset:34816
	ds_read_b128 v[190:193], v215 offset:36864
	ds_read_b128 v[194:197], v215 offset:38912
	v_mfma_f32_16x16x32_bf16 v[60:63], v[162:165], v[198:201], v[60:63]
	v_mfma_f32_16x16x32_bf16 v[56:59], v[162:165], v[202:205], v[56:59]
	s_add_u32 s50, s48, s12
	s_addc_u32 s51, s49, s13
	s_mov_b32 m0, s62
	v_lshl_add_u64 v[178:179], v[134:135], 0, s[50:51]
	global_load_lds_dwordx4 v[178:179], off sc1
	v_mfma_f32_16x16x32_bf16 v[52:55], v[162:165], v[206:209], v[52:55]
	v_mfma_f32_16x16x32_bf16 v[44:47], v[162:165], v[210:213], v[44:47]
	s_add_u32 s50, s48, s14
	s_addc_u32 s51, s49, s15
	s_add_u32 m0, s62, 0x2000
	v_lshl_add_u64 v[178:179], v[134:135], 0, s[50:51]
	global_load_lds_dwordx4 v[178:179], off sc1
	v_mfma_f32_16x16x32_bf16 v[36:39], v[166:169], v[198:201], v[36:39]
	v_mfma_f32_16x16x32_bf16 v[32:35], v[166:169], v[202:205], v[32:35]
	s_add_u32 s50, s48, s16
	s_addc_u32 s51, s49, s17
	s_add_u32 m0, s62, 0x4000
	v_lshl_add_u64 v[178:179], v[134:135], 0, s[50:51]
	global_load_lds_dwordx4 v[178:179], off sc1
	v_mfma_f32_16x16x32_bf16 v[28:31], v[166:169], v[206:209], v[28:31]
	v_mfma_f32_16x16x32_bf16 v[24:27], v[166:169], v[210:213], v[24:27]
	s_add_u32 s50, s48, s18
	s_addc_u32 s51, s49, s19
	s_add_u32 m0, s62, 0x6000
	v_lshl_add_u64 v[178:179], v[134:135], 0, s[50:51]
	global_load_lds_dwordx4 v[178:179], off sc1
	v_mfma_f32_16x16x32_bf16 v[20:23], v[170:173], v[198:201], v[20:23]
	v_mfma_f32_16x16x32_bf16 v[16:19], v[170:173], v[202:205], v[16:19]
	s_add_u32 s50, s48, s22
	s_addc_u32 s51, s49, s23
	s_add_u32 m0, s62, 0x8000
	v_lshl_add_u64 v[178:179], v[132:133], 0, s[50:51]
	global_load_lds_dwordx4 v[178:179], off sc1
	v_mfma_f32_16x16x32_bf16 v[12:15], v[170:173], v[206:209], v[12:15]
	v_mfma_f32_16x16x32_bf16 v[8:11], v[170:173], v[210:213], v[8:11]
	s_add_u32 s50, s48, s36
	s_addc_u32 s51, s49, s37
	s_add_u32 m0, s62, 0xa000
	v_lshl_add_u64 v[178:179], v[132:133], 0, s[50:51]
	global_load_lds_dwordx4 v[178:179], off sc1
	v_mfma_f32_16x16x32_bf16 v[4:7], v[174:177], v[198:201], v[4:7]
	v_mfma_f32_16x16x32_bf16 v[0:3], v[174:177], v[202:205], v[0:3]
	s_add_u32 s50, s48, s40
	s_addc_u32 s51, s49, s41
	s_add_u32 m0, s62, 0xc000
	v_lshl_add_u64 v[178:179], v[132:133], 0, s[50:51]
	global_load_lds_dwordx4 v[178:179], off sc1
	v_mfma_f32_16x16x32_bf16 v[48:51], v[174:177], v[206:209], v[48:51]
	v_mfma_f32_16x16x32_bf16 v[40:43], v[174:177], v[210:213], v[40:43]
	s_add_u32 s50, s48, s42
	s_addc_u32 s51, s49, s43
	s_add_u32 m0, s62, 0xe000
	v_lshl_add_u64 v[178:179], v[132:133], 0, s[50:51]
	global_load_lds_dwordx4 v[178:179], off sc1

.LBB0_660:
	s_ashr_i32 s96, s94, 3
	s_and_b32 s21, s94, 7
	s_and_b32 s70, s96, -8
	s_or_b32 s64, s70, s21
	s_lshl_b32 s20, s91, 11
	s_ashr_i32 s65, s64, 31
	v_mov_b32_e32 v6, v181
	s_and_b32 s97, s93, 7
	s_bfe_u32 s6, s91, 0x30008
	s_and_b32 s20, s20, 0x380000
	s_lshl_b64 s[66:67], s[64:65], 19
	s_add_u32 s66, s3, s66
	v_lshrrev_b32_e32 v7, 4, v6
	v_lshlrev_b32_e32 v1, 6, v6
	v_xor_b32_e32 v0, v7, v6
	v_and_b32_e32 v8, 0x3c0, v1
	v_lshlrev_b32_e32 v1, 7, v6
	s_addc_u32 s67, s72, s67
	s_lshl_b32 s21, s94, 5
	v_lshlrev_b32_e32 v0, 3, v0
	v_and_b32_e32 v1, 0xfffffc00, v1
	s_and_b32 s95, s21, 0x700
	v_and_or_b32 v0, v0, 56, v1
	s_lshl_b32 s21, s95, 11
	v_ashrrev_i32_e32 v1, 31, v0
	v_lshl_add_u32 v142, v6, 4, 0
	s_add_u32 s68, s73, s21
	v_lshlrev_b64 v[0:1], 1, v[0:1]
	v_readfirstlane_b32 s21, v142
	v_add_u32_e32 v9, 0x2000, v142
	v_lshl_add_u64 v[2:3], s[66:67], 0, v[0:1]
	s_mov_b32 m0, s21
	v_readfirstlane_b32 s21, v9
	v_add_u32_e32 v9, 0x4000, v142
	s_waitcnt vmcnt(63) expcnt(7) lgkmcnt(15)
	s_barrier
	global_load_lds_dwordx4 v[2:3], off
	v_lshl_add_u64 v[4:5], v[2:3], 0, s[8:9]
	s_mov_b32 m0, s21
	v_readfirstlane_b32 s21, v9
	global_load_lds_dwordx4 v[4:5], off
	v_lshl_add_u64 v[4:5], v[2:3], 0, s[10:11]
	s_mov_b32 m0, s21
	s_addc_u32 s69, s74, 0
	global_load_lds_dwordx4 v[4:5], off
	v_add_u32_e32 v4, 0x6000, v142
	v_lshl_add_u64 v[2:3], v[2:3], 0, s[12:13]
	v_readfirstlane_b32 s21, v4
	v_add_u32_e32 v4, 0x8000, v142
	s_mov_b32 m0, s21
	v_readfirstlane_b32 s21, v4
	v_add_u32_e32 v9, 0xa000, v142
	global_load_lds_dwordx4 v[2:3], off
	v_lshl_add_u64 v[2:3], s[68:69], 0, v[0:1]
	s_mov_b32 m0, s21
	v_readfirstlane_b32 s21, v9
	v_add_u32_e32 v9, 0xc000, v142
	global_load_lds_dwordx4 v[2:3], off
	v_lshl_add_u64 v[4:5], v[2:3], 0, s[8:9]
	s_mov_b32 m0, s21
	v_readfirstlane_b32 s21, v9
	global_load_lds_dwordx4 v[4:5], off
	v_lshl_add_u64 v[4:5], v[2:3], 0, s[10:11]
	s_mov_b32 m0, s21
	v_lshl_add_u64 v[2:3], v[2:3], 0, s[12:13]
	global_load_lds_dwordx4 v[4:5], off
	v_add_u32_e32 v4, 0xe000, v142
	s_or_b32 s66, s70, s97
	v_readfirstlane_b32 s21, v4
	s_mov_b32 m0, s21
	v_ashrrev_i32_e32 v4, 6, v6
	global_load_lds_dwordx4 v[2:3], off
	v_lshrrev_b32_e32 v5, 30, v4
	s_ashr_i32 s67, s66, 31
	v_add_u32_e32 v5, v4, v5
	s_lshl_b64 s[68:69], s[66:67], 19
	v_bfe_u32 v2, v6, 4, 2
	v_bfe_u32 v3, v6, 1, 3
	v_and_b32_e32 v6, 0x7fffc, v5
	s_add_u32 s68, s34, s68
	v_sub_u32_e32 v4, v4, v6
	s_addc_u32 s69, s35, s69
	v_lshlrev_b32_e32 v144, 13, v4
	v_bitop3_b32 v4, v7, v3, 3 bitop3:0x6c
	v_bitop3_b32 v2, v2, v3, 4 bitop3:0x36
	v_lshl_add_u64 v[138:139], s[68:69], 0, v[0:1]
	s_add_u32 s68, s34, s20
	v_lshlrev_b32_e32 v5, 12, v5
	v_lshlrev_b32_e32 v4, 3, v4
	v_lshlrev_b32_e32 v2, 3, v2
	s_addc_u32 s69, s35, 0
	v_and_b32_e32 v143, 0xffffc000, v5
	v_lshl_add_u64 v[140:141], s[68:69], 0, v[0:1]
	s_mov_b64 s[68:69], 0
	v_lshlrev_b32_e32 v145, 1, v8
	v_lshlrev_b32_e32 v174, 1, v4
	v_lshlrev_b32_e32 v175, 1, v2
	s_mov_b32 vcc_lo, 0
	s_mov_b32 s86, 0
	v_mov_b32_e32 v4, 0
	v_mov_b32_e32 v5, v131
	v_mov_b32_e32 v6, v131
	v_mov_b32_e32 v7, v131
	v_mov_b32_e32 v12, 0
	v_mov_b32_e32 v13, v131
	v_mov_b32_e32 v14, v131
	v_mov_b32_e32 v15, v131
	v_mov_b32_e32 v0, 0
	v_mov_b32_e32 v1, v131
	v_mov_b32_e32 v2, v131
	v_mov_b32_e32 v3, v131
	v_mov_b32_e32 v8, 0
	v_mov_b32_e32 v9, v131
	v_mov_b32_e32 v10, v131
	v_mov_b32_e32 v11, v131
	v_mov_b32_e32 v16, 0
	v_mov_b32_e32 v17, v131
	v_mov_b32_e32 v18, v131
	v_mov_b32_e32 v19, v131
	v_mov_b32_e32 v20, 0
	v_mov_b32_e32 v21, v131
	v_mov_b32_e32 v22, v131
	v_mov_b32_e32 v23, v131
	v_mov_b32_e32 v24, 0
	v_mov_b32_e32 v25, v131
	v_mov_b32_e32 v26, v131
	v_mov_b32_e32 v27, v131
	v_mov_b32_e32 v28, 0
	v_mov_b32_e32 v29, v131
	v_mov_b32_e32 v30, v131
	v_mov_b32_e32 v31, v131
	v_mov_b32_e32 v32, 0
	v_mov_b32_e32 v33, v131
	v_mov_b32_e32 v34, v131
	v_mov_b32_e32 v35, v131
	v_mov_b32_e32 v36, 0
	v_mov_b32_e32 v37, v131
	v_mov_b32_e32 v38, v131
	v_mov_b32_e32 v39, v131
	v_mov_b32_e32 v40, 0
	v_mov_b32_e32 v41, v131
	v_mov_b32_e32 v42, v131
	v_mov_b32_e32 v43, v131
	v_mov_b32_e32 v44, 0
	v_mov_b32_e32 v45, v131
	v_mov_b32_e32 v46, v131
	v_mov_b32_e32 v47, v131
	v_mov_b32_e32 v48, 0
	v_mov_b32_e32 v49, v131
	v_mov_b32_e32 v50, v131
	v_mov_b32_e32 v51, v131
	v_mov_b32_e32 v52, 0
	v_mov_b32_e32 v53, v131
	v_mov_b32_e32 v54, v131
	v_mov_b32_e32 v55, v131
	v_mov_b32_e32 v56, 0
	v_mov_b32_e32 v57, v131
	v_mov_b32_e32 v58, v131
	v_mov_b32_e32 v59, v131
	v_mov_b32_e32 v60, 0
	v_mov_b32_e32 v61, v131
	v_mov_b32_e32 v62, v131
	v_mov_b32_e32 v63, v131
	v_mov_b32_e32 v64, 0
	v_mov_b32_e32 v65, v131
	v_mov_b32_e32 v66, v131
	v_mov_b32_e32 v67, v131
	v_mov_b32_e32 v68, 0
	v_mov_b32_e32 v69, v131
	v_mov_b32_e32 v70, v131
	v_mov_b32_e32 v71, v131
	v_mov_b32_e32 v72, 0
	v_mov_b32_e32 v73, v131
	v_mov_b32_e32 v74, v131
	v_mov_b32_e32 v75, v131
	v_mov_b32_e32 v76, 0
	v_mov_b32_e32 v77, v131
	v_mov_b32_e32 v78, v131
	v_mov_b32_e32 v79, v131
	v_mov_b32_e32 v80, 0
	v_mov_b32_e32 v81, v131
	v_mov_b32_e32 v82, v131
	v_mov_b32_e32 v83, v131
	v_mov_b32_e32 v84, 0
	v_mov_b32_e32 v85, v131
	v_mov_b32_e32 v86, v131
	v_mov_b32_e32 v87, v131
	v_mov_b32_e32 v88, 0
	v_mov_b32_e32 v89, v131
	v_mov_b32_e32 v90, v131
	v_mov_b32_e32 v91, v131
	v_mov_b32_e32 v92, 0
	v_mov_b32_e32 v93, v131
	v_mov_b32_e32 v94, v131
	v_mov_b32_e32 v95, v131
	v_mov_b32_e32 v96, 0
	v_mov_b32_e32 v97, v131
	v_mov_b32_e32 v98, v131
	v_mov_b32_e32 v99, v131
	v_mov_b32_e32 v100, 0
	v_mov_b32_e32 v101, v131
	v_mov_b32_e32 v102, v131
	v_mov_b32_e32 v103, v131
	v_mov_b32_e32 v104, 0
	v_mov_b32_e32 v105, v131
	v_mov_b32_e32 v106, v131
	v_mov_b32_e32 v107, v131
	v_mov_b32_e32 v108, 0
	v_mov_b32_e32 v109, v131
	v_mov_b32_e32 v110, v131
	v_mov_b32_e32 v111, v131
	v_mov_b32_e32 v112, 0
	v_mov_b32_e32 v113, v131
	v_mov_b32_e32 v114, v131
	v_mov_b32_e32 v115, v131
	v_mov_b32_e32 v116, 0
	v_mov_b32_e32 v117, v131
	v_mov_b32_e32 v118, v131
	v_mov_b32_e32 v119, v131
	v_mov_b32_e32 v120, 0
	v_mov_b32_e32 v121, v131
	v_mov_b32_e32 v122, v131
	v_mov_b32_e32 v123, v131
	v_mov_b32_e32 v124, 0
	v_mov_b32_e32 v125, v131
	v_mov_b32_e32 v126, v131
	v_mov_b32_e32 v127, v131
	s_waitcnt vmcnt(0) lgkmcnt(0)
	s_barrier
	v_add3_u32 v180, v143, v145, v174
	v_add3_u32 v245, v144, v145, v174
	v_add3_u32 v244, v143, v145, v175
	v_add3_u32 v246, v144, v145, v175
	v_readfirstlane_b32 s87, v142
	ds_read_b128 v[176:179], v180
	ds_read_b128 v[182:185], v180 offset:2048
	ds_read_b128 v[186:189], v180 offset:4096
	ds_read_b128 v[190:193], v180 offset:6144
	ds_read_b128 v[210:213], v245 offset:32768
	ds_read_b128 v[214:217], v245 offset:34816
	ds_read_b128 v[218:221], v245 offset:36864
	ds_read_b128 v[222:225], v245 offset:38912
	s_mov_b32 s86, 0
	s_mov_b64 s[68:69], 0
	s_add_u32 s87, s87, 0x10000
	s_add_u32 s70, s68, 0x4000080
	s_addc_u32 s71, s69, 0
	s_mov_b32 m0, s87
	v_lshl_add_u64 v[242:243], v[138:139], 0, s[70:71]
	global_load_lds_dwordx4 v[242:243], off sc1
	s_add_u32 s70, s68, 0x4020080
	s_addc_u32 s71, s69, 0
	s_add_u32 m0, s87, 0x2000
	v_lshl_add_u64 v[242:243], v[138:139], 0, s[70:71]
	global_load_lds_dwordx4 v[242:243], off sc1
	s_add_u32 s70, s68, 0x4040080
	s_addc_u32 s71, s69, 0
	s_add_u32 m0, s87, 0x4000
	v_lshl_add_u64 v[242:243], v[138:139], 0, s[70:71]
	global_load_lds_dwordx4 v[242:243], off sc1
	s_add_u32 s70, s68, s14
	s_addc_u32 s71, s69, s15
	s_add_u32 m0, s87, 0x6000
	v_lshl_add_u64 v[242:243], v[138:139], 0, s[70:71]
	global_load_lds_dwordx4 v[242:243], off sc1
	s_add_u32 s70, s68, s16
	s_addc_u32 s71, s69, s17
	s_add_u32 m0, s87, 0x8000
	v_lshl_add_u64 v[242:243], v[140:141], 0, s[70:71]
	global_load_lds_dwordx4 v[242:243], off sc1
	s_add_u32 s70, s68, s18
	s_addc_u32 s71, s69, s19
	s_add_u32 m0, s87, 0xa000
	v_lshl_add_u64 v[242:243], v[140:141], 0, s[70:71]
	global_load_lds_dwordx4 v[242:243], off sc1
	s_add_u32 s70, s68, s22
	s_addc_u32 s71, s69, s23
	s_add_u32 m0, s87, 0xc000
	v_lshl_add_u64 v[242:243], v[140:141], 0, s[70:71]
	global_load_lds_dwordx4 v[242:243], off sc1
	s_add_u32 s70, s68, s36
	s_addc_u32 s71, s69, s37
	s_add_u32 m0, s87, 0xe000
	v_lshl_add_u64 v[242:243], v[140:141], 0, s[70:71]
	global_load_lds_dwordx4 v[242:243], off sc1
	s_branch .Lg5_entry
.Lg5_top:
	s_waitcnt lgkmcnt(0)
	s_waitcnt vmcnt(0)
	s_barrier
	v_xor_b32_e32 v180, 0x10000, v180
	v_xor_b32_e32 v245, 0x10000, v245
	v_xor_b32_e32 v244, 0x10000, v244
	v_xor_b32_e32 v246, 0x10000, v246
	s_xor_b32 s87, s87, 0x10000
	ds_read_b128 v[176:179], v180
	ds_read_b128 v[182:185], v180 offset:2048
	ds_read_b128 v[186:189], v180 offset:4096
	ds_read_b128 v[190:193], v180 offset:6144
	ds_read_b128 v[210:213], v245 offset:32768
	ds_read_b128 v[214:217], v245 offset:34816
	ds_read_b128 v[218:221], v245 offset:36864
	ds_read_b128 v[222:225], v245 offset:38912
	v_mfma_f32_16x16x32_bf16 v[60:63], v[194:197], v[226:229], v[60:63]
	v_mfma_f32_16x16x32_bf16 v[56:59], v[194:197], v[230:233], v[56:59]
	s_add_u32 s70, s68, 0x4000080
	s_addc_u32 s71, s69, 0
	s_mov_b32 m0, s87
	v_lshl_add_u64 v[242:243], v[138:139], 0, s[70:71]
	global_load_lds_dwordx4 v[242:243], off sc1
	v_mfma_f32_16x16x32_bf16 v[52:55], v[194:197], v[234:237], v[52:55]
	v_mfma_f32_16x16x32_bf16 v[48:51], v[194:197], v[238:241], v[48:51]
	s_add_u32 s70, s68, 0x4020080
	s_addc_u32 s71, s69, 0
	s_add_u32 m0, s87, 0x2000
	v_lshl_add_u64 v[242:243], v[138:139], 0, s[70:71]
	global_load_lds_dwordx4 v[242:243], off sc1
	v_mfma_f32_16x16x32_bf16 v[44:47], v[198:201], v[226:229], v[44:47]
	v_mfma_f32_16x16x32_bf16 v[40:43], v[198:201], v[230:233], v[40:43]
	s_add_u32 s70, s68, 0x4040080
	s_addc_u32 s71, s69, 0
	s_add_u32 m0, s87, 0x4000
	v_lshl_add_u64 v[242:243], v[138:139], 0, s[70:71]
	global_load_lds_dwordx4 v[242:243], off sc1
	v_mfma_f32_16x16x32_bf16 v[36:39], v[198:201], v[234:237], v[36:39]
	v_mfma_f32_16x16x32_bf16 v[32:35], v[198:201], v[238:241], v[32:35]
	s_add_u32 s70, s68, s14
	s_addc_u32 s71, s69, s15
	s_add_u32 m0, s87, 0x6000
	v_lshl_add_u64 v[242:243], v[138:139], 0, s[70:71]
	global_load_lds_dwordx4 v[242:243], off sc1
	v_mfma_f32_16x16x32_bf16 v[28:31], v[202:205], v[226:229], v[28:31]
	v_mfma_f32_16x16x32_bf16 v[24:27], v[202:205], v[230:233], v[24:27]
	s_add_u32 s70, s68, s16
	s_addc_u32 s71, s69, s17
	s_add_u32 m0, s87, 0x8000
	v_lshl_add_u64 v[242:243], v[140:141], 0, s[70:71]
	global_load_lds_dwordx4 v[242:243], off sc1
	v_mfma_f32_16x16x32_bf16 v[20:23], v[202:205], v[234:237], v[20:23]
	v_mfma_f32_16x16x32_bf16 v[16:19], v[202:205], v[238:241], v[16:19]
	s_add_u32 s70, s68, s18
	s_addc_u32 s71, s69, s19
	s_add_u32 m0, s87, 0xa000
	v_lshl_add_u64 v[242:243], v[140:141], 0, s[70:71]
	global_load_lds_dwordx4 v[242:243], off sc1
	v_mfma_f32_16x16x32_bf16 v[8:11], v[206:209], v[226:229], v[8:11]
	v_mfma_f32_16x16x32_bf16 v[0:3], v[206:209], v[230:233], v[0:3]
	s_add_u32 s70, s68, s22
	s_addc_u32 s71, s69, s23
	s_add_u32 m0, s87, 0xc000
	v_lshl_add_u64 v[242:243], v[140:141], 0, s[70:71]
	global_load_lds_dwordx4 v[242:243], off sc1
	v_mfma_f32_16x16x32_bf16 v[12:15], v[206:209], v[234:237], v[12:15]
	v_mfma_f32_16x16x32_bf16 v[4:7], v[206:209], v[238:241], v[4:7]
	s_add_u32 s70, s68, s36
	s_addc_u32 s71, s69, s37
	s_add_u32 m0, s87, 0xe000
	v_lshl_add_u64 v[242:243], v[140:141], 0, s[70:71]
	global_load_lds_dwordx4 v[242:243], off sc1

.LBB0_667:
	ds_read_b128 v[2:5], v0
	v_lshl_add_u64 v[6:7], v[138:139], 0, s[68:69]
	v_add_co_u32_e32 v8, vcc, 0x6000000, v6
	s_add_u32 s68, s68, 0x20000
	s_nop 0
	v_addc_co_u32_e32 v9, vcc, 0, v7, vcc
	s_waitcnt lgkmcnt(0)
	global_store_dwordx4 v[8:9], v[2:5], off sc1
	ds_read_b128 v[2:5], v0 offset:1152
	v_add_co_u32_e32 v8, vcc, 0x6008000, v6
	s_addc_u32 s69, s69, 0
	s_nop 0
	v_addc_co_u32_e32 v9, vcc, 0, v7, vcc
	s_waitcnt lgkmcnt(0)
	global_store_dwordx4 v[8:9], v[2:5], off sc1
	ds_read_b128 v[2:5], v0 offset:2304
	v_add_co_u32_e32 v8, vcc, 0x6010000, v6
	s_cmp_lg_u32 s68, 0x80000
	s_nop 0
	v_addc_co_u32_e32 v9, vcc, 0, v7, vcc
	s_waitcnt lgkmcnt(0)
	global_store_dwordx4 v[8:9], v[2:5], off sc1
	ds_read_b128 v[2:5], v0 offset:3456
	v_add_co_u32_e32 v6, vcc, 0x6018000, v6
	v_add_u32_e32 v0, 0x1200, v0
	s_nop 0
	v_addc_co_u32_e32 v7, vcc, 0, v7, vcc
	s_waitcnt lgkmcnt(0)
	global_store_dwordx4 v[6:7], v[2:5], off sc1
	s_cbranch_scc1 .LBB0_667
	v_mov_b32_e32 v6, v181
	s_waitcnt lgkmcnt(0)
	s_lshl_b32 s68, s6, 20
	v_lshrrev_b32_e32 v7, 4, v6
	v_lshlrev_b32_e32 v1, 6, v6
	v_xor_b32_e32 v0, v7, v6
	v_and_b32_e32 v8, 0x3c0, v1
	v_lshlrev_b32_e32 v1, 8, v6
	v_lshlrev_b32_e32 v0, 3, v0
	v_and_b32_e32 v1, 0xfffff800, v1
	s_lshl_b64 s[20:21], s[64:65], 20
	v_and_or_b32 v0, v0, 56, v1
	s_add_u32 s20, s75, s20
	v_ashrrev_i32_e32 v1, 31, v0
	s_addc_u32 s21, s88, s21
	v_lshlrev_b64 v[0:1], 1, v[0:1]
	v_lshl_add_u32 v174, v6, 4, 0
	v_lshl_add_u64 v[2:3], s[20:21], 0, v[0:1]
	v_readfirstlane_b32 s20, v174
	v_add_u32_e32 v9, 0x2000, v174
	s_mov_b32 m0, s20
	v_readfirstlane_b32 s20, v9
	v_add_u32_e32 v9, 0x4000, v174
	s_barrier
	global_load_lds_dwordx4 v[2:3], off
	v_lshl_add_u64 v[4:5], v[2:3], 0, s[10:11]
	s_mov_b32 m0, s20
	v_readfirstlane_b32 s20, v9
	global_load_lds_dwordx4 v[4:5], off
	v_lshl_add_u64 v[4:5], v[2:3], 0, s[40:41]
	s_mov_b32 m0, s20
	s_lshl_b32 s64, s95, 12
	global_load_lds_dwordx4 v[4:5], off
	v_add_u32_e32 v4, 0x6000, v174
	s_add_u32 s64, s89, s64
	v_readfirstlane_b32 s20, v4
	v_add_u32_e32 v4, 0x8000, v174
	s_addc_u32 s65, s90, 0
	v_lshl_add_u64 v[2:3], v[2:3], 0, s[42:43]
	s_mov_b32 m0, s20
	v_readfirstlane_b32 s20, v4
	v_add_u32_e32 v9, 0xa000, v174
	global_load_lds_dwordx4 v[2:3], off
	v_lshl_add_u64 v[2:3], s[64:65], 0, v[0:1]
	s_mov_b32 m0, s20
	v_readfirstlane_b32 s20, v9
	v_add_u32_e32 v9, 0xc000, v174
	global_load_lds_dwordx4 v[2:3], off
	v_lshl_add_u64 v[4:5], v[2:3], 0, s[10:11]
	s_mov_b32 m0, s20
	v_readfirstlane_b32 s20, v9
	global_load_lds_dwordx4 v[4:5], off
	v_lshl_add_u64 v[4:5], v[2:3], 0, s[40:41]
	s_mov_b32 m0, s20
	v_lshl_add_u64 v[2:3], v[2:3], 0, s[42:43]
	global_load_lds_dwordx4 v[4:5], off
	v_add_u32_e32 v4, 0xe000, v174
	s_mov_b32 s69, 0
	v_readfirstlane_b32 s20, v4
	s_mov_b32 m0, s20
	v_ashrrev_i32_e32 v4, 6, v6
	global_load_lds_dwordx4 v[2:3], off
	v_lshrrev_b32_e32 v5, 30, v4
	v_add_u32_e32 v5, v4, v5
	s_lshl_b64 s[20:21], s[66:67], 20
	v_bfe_u32 v2, v6, 4, 2
	v_bfe_u32 v3, v6, 1, 3
	v_and_b32_e32 v6, 0x7fffc, v5
	s_add_u32 s20, s34, s20
	v_sub_u32_e32 v4, v4, v6
	s_addc_u32 s21, s35, s21
	v_lshlrev_b32_e32 v5, 12, v5
	v_lshlrev_b32_e32 v176, 13, v4
	v_bitop3_b32 v4, v7, v3, 3 bitop3:0x6c
	v_bitop3_b32 v2, v2, v3, 4 bitop3:0x36
	v_lshl_add_u64 v[142:143], s[20:21], 0, v[0:1]
	s_add_u32 s20, s34, s68
	v_and_b32_e32 v175, 0xffffc000, v5
	v_lshlrev_b32_e32 v5, 3, v4
	v_lshlrev_b32_e32 v2, 3, v2
	s_addc_u32 s21, s35, 0
	v_mov_b32_e32 v4, 0
	v_lshl_add_u64 v[144:145], s[20:21], 0, v[0:1]
	s_mov_b64 s[64:65], 0
	v_lshlrev_b32_e32 v177, 1, v8
	v_lshlrev_b32_e32 v178, 1, v5
	v_lshlrev_b32_e32 v179, 1, v2
	s_mov_b32 s68, 0
	v_mov_b32_e32 v5, v4
	v_mov_b32_e32 v6, v4
	v_mov_b32_e32 v7, v4
	v_mov_b32_e32 v8, v4
	v_mov_b32_e32 v9, v4
	v_mov_b32_e32 v10, v4
	v_mov_b32_e32 v11, v4
	v_mov_b32_e32 v0, v4
	v_mov_b32_e32 v1, v4
	v_mov_b32_e32 v2, v4
	v_mov_b32_e32 v3, v4
	v_mov_b32_e32 v12, v4
	v_mov_b32_e32 v13, v4
	v_mov_b32_e32 v14, v4
	v_mov_b32_e32 v15, v4
	v_mov_b32_e32 v16, v4
	v_mov_b32_e32 v17, v4
	v_mov_b32_e32 v18, v4
	v_mov_b32_e32 v19, v4
	v_mov_b32_e32 v20, v4
	v_mov_b32_e32 v21, v4
	v_mov_b32_e32 v22, v4
	v_mov_b32_e32 v23, v4
	v_mov_b32_e32 v24, v4
	v_mov_b32_e32 v25, v4
	v_mov_b32_e32 v26, v4
	v_mov_b32_e32 v27, v4
	v_mov_b32_e32 v28, v4
	v_mov_b32_e32 v29, v4
	v_mov_b32_e32 v30, v4
	v_mov_b32_e32 v31, v4
	v_mov_b32_e32 v32, v4
	v_mov_b32_e32 v33, v4
	v_mov_b32_e32 v34, v4
	v_mov_b32_e32 v35, v4
	v_mov_b32_e32 v36, v4
	v_mov_b32_e32 v37, v4
	v_mov_b32_e32 v38, v4
	v_mov_b32_e32 v39, v4
	v_mov_b32_e32 v40, v4
	v_mov_b32_e32 v41, v4
	v_mov_b32_e32 v42, v4
	v_mov_b32_e32 v43, v4
	v_mov_b32_e32 v44, v4
	v_mov_b32_e32 v45, v4
	v_mov_b32_e32 v46, v4
	v_mov_b32_e32 v47, v4
	v_mov_b32_e32 v48, v4
	v_mov_b32_e32 v49, v4
	v_mov_b32_e32 v50, v4
	v_mov_b32_e32 v51, v4
	v_mov_b32_e32 v52, v4
	v_mov_b32_e32 v53, v4
	v_mov_b32_e32 v54, v4
	v_mov_b32_e32 v55, v4
	v_mov_b32_e32 v56, v4
	v_mov_b32_e32 v57, v4
	v_mov_b32_e32 v58, v4
	v_mov_b32_e32 v59, v4
	v_mov_b32_e32 v60, v4
	v_mov_b32_e32 v61, v4
	v_mov_b32_e32 v62, v4
	v_mov_b32_e32 v63, v4
	v_mov_b32_e32 v64, v4
	v_mov_b32_e32 v65, v4
	v_mov_b32_e32 v66, v4
	v_mov_b32_e32 v67, v4
	v_mov_b32_e32 v68, v4
	v_mov_b32_e32 v69, v4
	v_mov_b32_e32 v70, v4
	v_mov_b32_e32 v71, v4
	v_mov_b32_e32 v72, v4
	v_mov_b32_e32 v73, v4
	v_mov_b32_e32 v74, v4
	v_mov_b32_e32 v75, v4
	v_mov_b32_e32 v76, v4
	v_mov_b32_e32 v77, v4
	v_mov_b32_e32 v78, v4
	v_mov_b32_e32 v79, v4
	v_mov_b32_e32 v80, v4
	v_mov_b32_e32 v81, v4
	v_mov_b32_e32 v82, v4
	v_mov_b32_e32 v83, v4
	v_mov_b32_e32 v84, v4
	v_mov_b32_e32 v85, v4
	v_mov_b32_e32 v86, v4
	v_mov_b32_e32 v87, v4
	v_mov_b32_e32 v88, v4
	v_mov_b32_e32 v89, v4
	v_mov_b32_e32 v90, v4
	v_mov_b32_e32 v91, v4
	v_mov_b32_e32 v92, v4
	v_mov_b32_e32 v93, v4
	v_mov_b32_e32 v94, v4
	v_mov_b32_e32 v95, v4
	v_mov_b32_e32 v96, v4
	v_mov_b32_e32 v97, v4
	v_mov_b32_e32 v98, v4
	v_mov_b32_e32 v99, v4
	v_mov_b32_e32 v100, v4
	v_mov_b32_e32 v101, v4
	v_mov_b32_e32 v102, v4
	v_mov_b32_e32 v103, v4
	v_mov_b32_e32 v104, v4
	v_mov_b32_e32 v105, v4
	v_mov_b32_e32 v106, v4
	v_mov_b32_e32 v107, v4
	v_mov_b32_e32 v108, v4
	v_mov_b32_e32 v109, v4
	v_mov_b32_e32 v110, v4
	v_mov_b32_e32 v111, v4
	v_mov_b32_e32 v112, v4
	v_mov_b32_e32 v113, v4
	v_mov_b32_e32 v114, v4
	v_mov_b32_e32 v115, v4
	v_mov_b32_e32 v116, v4
	v_mov_b32_e32 v117, v4
	v_mov_b32_e32 v118, v4
	v_mov_b32_e32 v119, v4
	v_mov_b32_e32 v120, v4
	v_mov_b32_e32 v121, v4
	v_mov_b32_e32 v122, v4
	v_mov_b32_e32 v123, v4
	v_mov_b32_e32 v124, v4
	v_mov_b32_e32 v125, v4
	v_mov_b32_e32 v126, v4
	v_mov_b32_e32 v127, v4
	s_waitcnt vmcnt(0) lgkmcnt(0)
	s_barrier
	v_add3_u32 v180, v175, v177, v178
	v_add3_u32 v249, v176, v177, v178
	v_add3_u32 v248, v175, v177, v179
	v_add3_u32 v250, v176, v177, v179
	v_readfirstlane_b32 s69, v174
	ds_read_b128 v[182:185], v180
	ds_read_b128 v[186:189], v180 offset:2048
	ds_read_b128 v[190:193], v180 offset:4096
	ds_read_b128 v[194:197], v180 offset:6144
	ds_read_b128 v[214:217], v249 offset:32768
	ds_read_b128 v[218:221], v249 offset:34816
	ds_read_b128 v[222:225], v249 offset:36864
	ds_read_b128 v[226:229], v249 offset:38912
	s_mov_b32 s68, 0
	s_mov_b64 s[64:65], 0
	s_add_u32 s69, s69, 0x10000
	s_add_u32 s66, s64, s44
	s_addc_u32 s67, s65, s45
	s_mov_b32 m0, s69
	v_lshl_add_u64 v[246:247], v[142:143], 0, s[66:67]
	global_load_lds_dwordx4 v[246:247], off sc1
	s_add_u32 s66, s64, s46
	s_addc_u32 s67, s65, s47
	s_add_u32 m0, s69, 0x2000
	v_lshl_add_u64 v[246:247], v[142:143], 0, s[66:67]
	global_load_lds_dwordx4 v[246:247], off sc1
	s_add_u32 s66, s64, s48
	s_addc_u32 s67, s65, s49
	s_add_u32 m0, s69, 0x4000
	v_lshl_add_u64 v[246:247], v[142:143], 0, s[66:67]
	global_load_lds_dwordx4 v[246:247], off sc1
	s_add_u32 s66, s64, s50
	s_addc_u32 s67, s65, s51
	s_add_u32 m0, s69, 0x6000
	v_lshl_add_u64 v[246:247], v[142:143], 0, s[66:67]
	global_load_lds_dwordx4 v[246:247], off sc1
	s_add_u32 s66, s64, s52
	s_addc_u32 s67, s65, s53
	s_add_u32 m0, s69, 0x8000
	v_lshl_add_u64 v[246:247], v[144:145], 0, s[66:67]
	global_load_lds_dwordx4 v[246:247], off sc1
	s_add_u32 s66, s64, s54
	s_addc_u32 s67, s65, s55
	s_add_u32 m0, s69, 0xa000
	v_lshl_add_u64 v[246:247], v[144:145], 0, s[66:67]
	global_load_lds_dwordx4 v[246:247], off sc1
	s_add_u32 s66, s64, s60
	s_addc_u32 s67, s65, s61
	s_add_u32 m0, s69, 0xc000
	v_lshl_add_u64 v[246:247], v[144:145], 0, s[66:67]
	global_load_lds_dwordx4 v[246:247], off sc1
	s_add_u32 s66, s64, s62
	s_addc_u32 s67, s65, s63
	s_add_u32 m0, s69, 0xe000
	v_lshl_add_u64 v[246:247], v[144:145], 0, s[66:67]
	global_load_lds_dwordx4 v[246:247], off sc1
	s_branch .Lg6_entry
.Lg6_top:
	s_waitcnt lgkmcnt(0)
	s_waitcnt vmcnt(0)
	s_barrier
	v_xor_b32_e32 v180, 0x10000, v180
	v_xor_b32_e32 v249, 0x10000, v249
	v_xor_b32_e32 v248, 0x10000, v248
	v_xor_b32_e32 v250, 0x10000, v250
	s_xor_b32 s69, s69, 0x10000
	ds_read_b128 v[182:185], v180
	ds_read_b128 v[186:189], v180 offset:2048
	ds_read_b128 v[190:193], v180 offset:4096
	ds_read_b128 v[194:197], v180 offset:6144
	ds_read_b128 v[214:217], v249 offset:32768
	ds_read_b128 v[218:221], v249 offset:34816
	ds_read_b128 v[222:225], v249 offset:36864
	ds_read_b128 v[226:229], v249 offset:38912
	v_mfma_f32_16x16x32_bf16 v[60:63], v[198:201], v[230:233], v[60:63]
	v_mfma_f32_16x16x32_bf16 v[56:59], v[198:201], v[234:237], v[56:59]
	s_add_u32 s66, s64, s44
	s_addc_u32 s67, s65, s45
	s_mov_b32 m0, s69
	v_lshl_add_u64 v[246:247], v[142:143], 0, s[66:67]
	global_load_lds_dwordx4 v[246:247], off sc1
	v_mfma_f32_16x16x32_bf16 v[52:55], v[198:201], v[238:241], v[52:55]
	v_mfma_f32_16x16x32_bf16 v[48:51], v[198:201], v[242:245], v[48:51]
	s_add_u32 s66, s64, s46
	s_addc_u32 s67, s65, s47
	s_add_u32 m0, s69, 0x2000
	v_lshl_add_u64 v[246:247], v[142:143], 0, s[66:67]
	global_load_lds_dwordx4 v[246:247], off sc1
	v_mfma_f32_16x16x32_bf16 v[44:47], v[202:205], v[230:233], v[44:47]
	v_mfma_f32_16x16x32_bf16 v[40:43], v[202:205], v[234:237], v[40:43]
	s_add_u32 s66, s64, s48
	s_addc_u32 s67, s65, s49
	s_add_u32 m0, s69, 0x4000
	v_lshl_add_u64 v[246:247], v[142:143], 0, s[66:67]
	global_load_lds_dwordx4 v[246:247], off sc1
	v_mfma_f32_16x16x32_bf16 v[36:39], v[202:205], v[238:241], v[36:39]
	v_mfma_f32_16x16x32_bf16 v[32:35], v[202:205], v[242:245], v[32:35]
	s_add_u32 s66, s64, s50
	s_addc_u32 s67, s65, s51
	s_add_u32 m0, s69, 0x6000
	v_lshl_add_u64 v[246:247], v[142:143], 0, s[66:67]
	global_load_lds_dwordx4 v[246:247], off sc1
	v_mfma_f32_16x16x32_bf16 v[28:31], v[206:209], v[230:233], v[28:31]
	v_mfma_f32_16x16x32_bf16 v[24:27], v[206:209], v[234:237], v[24:27]
	s_add_u32 s66, s64, s52
	s_addc_u32 s67, s65, s53
	s_add_u32 m0, s69, 0x8000
	v_lshl_add_u64 v[246:247], v[144:145], 0, s[66:67]
	global_load_lds_dwordx4 v[246:247], off sc1
	v_mfma_f32_16x16x32_bf16 v[20:23], v[206:209], v[238:241], v[20:23]
	v_mfma_f32_16x16x32_bf16 v[16:19], v[206:209], v[242:245], v[16:19]
	s_add_u32 s66, s64, s54
	s_addc_u32 s67, s65, s55
	s_add_u32 m0, s69, 0xa000
	v_lshl_add_u64 v[246:247], v[144:145], 0, s[66:67]
	global_load_lds_dwordx4 v[246:247], off sc1
	v_mfma_f32_16x16x32_bf16 v[12:15], v[210:213], v[230:233], v[12:15]
	v_mfma_f32_16x16x32_bf16 v[0:3], v[210:213], v[234:237], v[0:3]
	s_add_u32 s66, s64, s60
	s_addc_u32 s67, s65, s61
	s_add_u32 m0, s69, 0xc000
	v_lshl_add_u64 v[246:247], v[144:145], 0, s[66:67]
	global_load_lds_dwordx4 v[246:247], off sc1
	v_mfma_f32_16x16x32_bf16 v[8:11], v[210:213], v[238:241], v[8:11]
	v_mfma_f32_16x16x32_bf16 v[4:7], v[210:213], v[242:245], v[4:7]
	s_add_u32 s66, s64, s62
	s_addc_u32 s67, s65, s63
	s_add_u32 m0, s69, 0xe000
	v_lshl_add_u64 v[246:247], v[144:145], 0, s[66:67]
	global_load_lds_dwordx4 v[246:247], off sc1

.LBB0_746:
	s_ashr_i32 s20, s60, 2
	v_mov_b32_e32 v6, v181
	s_and_b32 s6, s60, 7
	s_and_b32 s51, s20, -8
	s_or_b32 s46, s51, s6
	v_lshrrev_b32_e32 v7, 4, v6
	v_lshlrev_b32_e32 v1, 6, v6
	v_xor_b32_e32 v0, v7, v6
	v_and_b32_e32 v8, 0x3c0, v1
	v_lshlrev_b32_e32 v1, 8, v6
	s_ashr_i32 s47, s46, 31
	v_lshlrev_b32_e32 v0, 3, v0
	v_and_b32_e32 v1, 0xfffff800, v1
	s_and_b32 s50, s55, 7
	s_bfe_u32 s6, s60, 0x20003
	s_lshl_b64 s[20:21], s[46:47], 20
	v_and_or_b32 v0, v0, 56, v1
	s_add_u32 s20, s3, s20
	v_ashrrev_i32_e32 v1, 31, v0
	s_addc_u32 s21, s52, s21
	v_lshlrev_b64 v[0:1], 1, v[0:1]
	v_lshl_add_u32 v134, v6, 4, 0
	v_lshl_add_u64 v[2:3], s[20:21], 0, v[0:1]
	v_readfirstlane_b32 s20, v134
	v_add_u32_e32 v9, 0x2000, v134
	s_mov_b32 m0, s20
	v_readfirstlane_b32 s20, v9
	v_add_u32_e32 v9, 0x4000, v134
	s_waitcnt vmcnt(63) expcnt(7) lgkmcnt(15)
	s_barrier
	global_load_lds_dwordx4 v[2:3], off
	v_lshl_add_u64 v[4:5], v[2:3], 0, s[8:9]
	s_mov_b32 m0, s20
	v_readfirstlane_b32 s20, v9
	global_load_lds_dwordx4 v[4:5], off
	v_lshl_add_u64 v[4:5], v[2:3], 0, s[10:11]
	s_mov_b32 m0, s20
	s_lshl_b32 s47, s6, 20
	global_load_lds_dwordx4 v[4:5], off
	v_add_u32_e32 v4, 0x6000, v134
	s_add_u32 s48, s53, s47
	v_readfirstlane_b32 s20, v4
	v_add_u32_e32 v4, 0x8000, v134
	s_addc_u32 s49, s54, 0
	v_lshl_add_u64 v[2:3], v[2:3], 0, s[12:13]
	s_mov_b32 m0, s20
	v_readfirstlane_b32 s20, v4
	v_add_u32_e32 v9, 0xa000, v134
	global_load_lds_dwordx4 v[2:3], off
	v_lshl_add_u64 v[2:3], s[48:49], 0, v[0:1]
	s_mov_b32 m0, s20
	v_readfirstlane_b32 s20, v9
	v_add_u32_e32 v9, 0xc000, v134
	global_load_lds_dwordx4 v[2:3], off
	v_lshl_add_u64 v[4:5], v[2:3], 0, s[8:9]
	s_mov_b32 m0, s20
	v_readfirstlane_b32 s20, v9
	global_load_lds_dwordx4 v[4:5], off
	v_lshl_add_u64 v[4:5], v[2:3], 0, s[10:11]
	s_mov_b32 m0, s20
	v_lshl_add_u64 v[2:3], v[2:3], 0, s[12:13]
	global_load_lds_dwordx4 v[4:5], off
	v_add_u32_e32 v4, 0xe000, v134
	v_mov_b32_e32 v36, 0
	v_readfirstlane_b32 s20, v4
	s_mov_b32 m0, s20
	v_ashrrev_i32_e32 v4, 6, v6
	global_load_lds_dwordx4 v[2:3], off
	s_or_b32 s20, s51, s50
	v_lshrrev_b32_e32 v5, 30, v4
	s_ashr_i32 s21, s20, 31
	v_add_u32_e32 v5, v4, v5
	s_lshl_b64 s[20:21], s[20:21], 20
	v_bfe_u32 v2, v6, 4, 2
	v_bfe_u32 v3, v6, 1, 3
	v_and_b32_e32 v6, 0x7fffc, v5
	s_add_u32 s20, s34, s20
	v_sub_u32_e32 v4, v4, v6
	s_addc_u32 s21, s35, s21
	v_lshlrev_b32_e32 v136, 13, v4
	v_bitop3_b32 v4, v7, v3, 3 bitop3:0x6c
	v_bitop3_b32 v2, v2, v3, 4 bitop3:0x36
	v_lshl_add_u64 v[130:131], s[20:21], 0, v[0:1]
	s_add_u32 s20, s34, s47
	v_lshlrev_b32_e32 v5, 12, v5
	v_lshlrev_b32_e32 v4, 3, v4
	v_lshlrev_b32_e32 v2, 3, v2
	s_addc_u32 s21, s35, 0
	v_and_b32_e32 v135, 0xffffc000, v5
	v_lshl_add_u64 v[132:133], s[20:21], 0, v[0:1]
	s_mov_b64 s[48:49], 0
	v_lshlrev_b32_e32 v137, 1, v8
	v_lshlrev_b32_e32 v138, 1, v4
	v_lshlrev_b32_e32 v139, 1, v2
	s_mov_b32 s61, 0
	s_mov_b32 s47, 0
	v_mov_b32_e32 v37, v36
	v_mov_b32_e32 v38, v36
	v_mov_b32_e32 v39, v36
	v_mov_b32_e32 v40, v36
	v_mov_b32_e32 v41, v36
	v_mov_b32_e32 v42, v36
	v_mov_b32_e32 v43, v36
	v_mov_b32_e32 v0, v36
	v_mov_b32_e32 v1, v36
	v_mov_b32_e32 v2, v36
	v_mov_b32_e32 v3, v36
	v_mov_b32_e32 v4, v36
	v_mov_b32_e32 v5, v36
	v_mov_b32_e32 v6, v36
	v_mov_b32_e32 v7, v36
	v_mov_b32_e32 v8, v36
	v_mov_b32_e32 v9, v36
	v_mov_b32_e32 v10, v36
	v_mov_b32_e32 v11, v36
	v_mov_b32_e32 v12, v36
	v_mov_b32_e32 v13, v36
	v_mov_b32_e32 v14, v36
	v_mov_b32_e32 v15, v36
	v_mov_b32_e32 v16, v36
	v_mov_b32_e32 v17, v36
	v_mov_b32_e32 v18, v36
	v_mov_b32_e32 v19, v36
	v_mov_b32_e32 v20, v36
	v_mov_b32_e32 v21, v36
	v_mov_b32_e32 v22, v36
	v_mov_b32_e32 v23, v36
	v_mov_b32_e32 v24, v36
	v_mov_b32_e32 v25, v36
	v_mov_b32_e32 v26, v36
	v_mov_b32_e32 v27, v36
	v_mov_b32_e32 v28, v36
	v_mov_b32_e32 v29, v36
	v_mov_b32_e32 v30, v36
	v_mov_b32_e32 v31, v36
	v_mov_b32_e32 v32, v36
	v_mov_b32_e32 v33, v36
	v_mov_b32_e32 v34, v36
	v_mov_b32_e32 v35, v36
	v_mov_b32_e32 v44, v36
	v_mov_b32_e32 v45, v36
	v_mov_b32_e32 v46, v36
	v_mov_b32_e32 v47, v36
	v_mov_b32_e32 v48, v36
	v_mov_b32_e32 v49, v36
	v_mov_b32_e32 v50, v36
	v_mov_b32_e32 v51, v36
	v_mov_b32_e32 v52, v36
	v_mov_b32_e32 v53, v36
	v_mov_b32_e32 v54, v36
	v_mov_b32_e32 v55, v36
	v_mov_b32_e32 v56, v36
	v_mov_b32_e32 v57, v36
	v_mov_b32_e32 v58, v36
	v_mov_b32_e32 v59, v36
	v_mov_b32_e32 v60, v36
	v_mov_b32_e32 v61, v36
	v_mov_b32_e32 v62, v36
	v_mov_b32_e32 v63, v36
	v_mov_b32_e32 v64, v36
	v_mov_b32_e32 v65, v36
	v_mov_b32_e32 v66, v36
	v_mov_b32_e32 v67, v36
	v_mov_b32_e32 v68, v36
	v_mov_b32_e32 v69, v36
	v_mov_b32_e32 v70, v36
	v_mov_b32_e32 v71, v36
	v_mov_b32_e32 v72, v36
	v_mov_b32_e32 v73, v36
	v_mov_b32_e32 v74, v36
	v_mov_b32_e32 v75, v36
	v_mov_b32_e32 v76, v36
	v_mov_b32_e32 v77, v36
	v_mov_b32_e32 v78, v36
	v_mov_b32_e32 v79, v36
	v_mov_b32_e32 v80, v36
	v_mov_b32_e32 v81, v36
	v_mov_b32_e32 v82, v36
	v_mov_b32_e32 v83, v36
	v_mov_b32_e32 v84, v36
	v_mov_b32_e32 v85, v36
	v_mov_b32_e32 v86, v36
	v_mov_b32_e32 v87, v36
	v_mov_b32_e32 v88, v36
	v_mov_b32_e32 v89, v36
	v_mov_b32_e32 v90, v36
	v_mov_b32_e32 v91, v36
	v_mov_b32_e32 v92, v36
	v_mov_b32_e32 v93, v36
	v_mov_b32_e32 v94, v36
	v_mov_b32_e32 v95, v36
	v_mov_b32_e32 v96, v36
	v_mov_b32_e32 v97, v36
	v_mov_b32_e32 v98, v36
	v_mov_b32_e32 v99, v36
	v_mov_b32_e32 v100, v36
	v_mov_b32_e32 v101, v36
	v_mov_b32_e32 v102, v36
	v_mov_b32_e32 v103, v36
	v_mov_b32_e32 v104, v36
	v_mov_b32_e32 v105, v36
	v_mov_b32_e32 v106, v36
	v_mov_b32_e32 v107, v36
	v_mov_b32_e32 v108, v36
	v_mov_b32_e32 v109, v36
	v_mov_b32_e32 v110, v36
	v_mov_b32_e32 v111, v36
	v_mov_b32_e32 v112, v36
	v_mov_b32_e32 v113, v36
	v_mov_b32_e32 v114, v36
	v_mov_b32_e32 v115, v36
	v_mov_b32_e32 v116, v36
	v_mov_b32_e32 v117, v36
	v_mov_b32_e32 v118, v36
	v_mov_b32_e32 v119, v36
	v_mov_b32_e32 v120, v36
	v_mov_b32_e32 v121, v36
	v_mov_b32_e32 v122, v36
	v_mov_b32_e32 v123, v36
	v_mov_b32_e32 v124, v36
	v_mov_b32_e32 v125, v36
	v_mov_b32_e32 v126, v36
	v_mov_b32_e32 v127, v36
	s_waitcnt vmcnt(0) lgkmcnt(0)
	s_barrier
	v_add3_u32 v141, v135, v137, v138
	v_add3_u32 v210, v136, v137, v138
	v_add3_u32 v180, v135, v137, v139
	v_add3_u32 v211, v136, v137, v139
	v_readfirstlane_b32 s61, v134
	ds_read_b128 v[142:145], v141
	ds_read_b128 v[146:149], v141 offset:2048
	ds_read_b128 v[150:153], v141 offset:4096
	ds_read_b128 v[154:157], v141 offset:6144
	ds_read_b128 v[174:177], v210 offset:32768
	ds_read_b128 v[182:185], v210 offset:34816
	ds_read_b128 v[186:189], v210 offset:36864
	ds_read_b128 v[190:193], v210 offset:38912
	s_mov_b32 s47, 0
	s_mov_b64 s[48:49], 0
	s_add_u32 s61, s61, 0x10000
	s_add_u32 s50, s48, s14
	s_addc_u32 s51, s49, s15
	s_mov_b32 m0, s61
	v_lshl_add_u64 v[178:179], v[130:131], 0, s[50:51]
	global_load_lds_dwordx4 v[178:179], off sc1
	s_add_u32 s50, s48, s16
	s_addc_u32 s51, s49, s17
	s_add_u32 m0, s61, 0x2000
	v_lshl_add_u64 v[178:179], v[130:131], 0, s[50:51]
	global_load_lds_dwordx4 v[178:179], off sc1
	s_add_u32 s50, s48, s18
	s_addc_u32 s51, s49, s19
	s_add_u32 m0, s61, 0x4000
	v_lshl_add_u64 v[178:179], v[130:131], 0, s[50:51]
	global_load_lds_dwordx4 v[178:179], off sc1
	s_add_u32 s50, s48, s22
	s_addc_u32 s51, s49, s23
	s_add_u32 m0, s61, 0x6000
	v_lshl_add_u64 v[178:179], v[130:131], 0, s[50:51]
	global_load_lds_dwordx4 v[178:179], off sc1
	s_add_u32 s50, s48, s36
	s_addc_u32 s51, s49, s37
	s_add_u32 m0, s61, 0x8000
	v_lshl_add_u64 v[178:179], v[132:133], 0, s[50:51]
	global_load_lds_dwordx4 v[178:179], off sc1
	s_add_u32 s50, s48, s40
	s_addc_u32 s51, s49, s41
	s_add_u32 m0, s61, 0xa000
	v_lshl_add_u64 v[178:179], v[132:133], 0, s[50:51]
	global_load_lds_dwordx4 v[178:179], off sc1
	s_add_u32 s50, s48, s42
	s_addc_u32 s51, s49, s43
	s_add_u32 m0, s61, 0xc000
	v_lshl_add_u64 v[178:179], v[132:133], 0, s[50:51]
	global_load_lds_dwordx4 v[178:179], off sc1
	s_add_u32 s50, s48, s44
	s_addc_u32 s51, s49, s45
	s_add_u32 m0, s61, 0xe000
	v_lshl_add_u64 v[178:179], v[132:133], 0, s[50:51]
	global_load_lds_dwordx4 v[178:179], off sc1
	s_branch .Lg7_entry
.Lg7_top:
	s_waitcnt lgkmcnt(0)
	s_waitcnt vmcnt(0)
	s_barrier
	v_xor_b32_e32 v141, 0x10000, v141
	v_xor_b32_e32 v210, 0x10000, v210
	v_xor_b32_e32 v180, 0x10000, v180
	v_xor_b32_e32 v211, 0x10000, v211
	s_xor_b32 s61, s61, 0x10000
	ds_read_b128 v[142:145], v141
	ds_read_b128 v[146:149], v141 offset:2048
	ds_read_b128 v[150:153], v141 offset:4096
	ds_read_b128 v[154:157], v141 offset:6144
	ds_read_b128 v[174:177], v210 offset:32768
	ds_read_b128 v[182:185], v210 offset:34816
	ds_read_b128 v[186:189], v210 offset:36864
	ds_read_b128 v[190:193], v210 offset:38912
	v_mfma_f32_16x16x32_bf16 v[60:63], v[158:161], v[194:197], v[60:63]
	v_mfma_f32_16x16x32_bf16 v[56:59], v[158:161], v[198:201], v[56:59]
	s_add_u32 s50, s48, s14
	s_addc_u32 s51, s49, s15
	s_mov_b32 m0, s61
	v_lshl_add_u64 v[178:179], v[130:131], 0, s[50:51]
	global_load_lds_dwordx4 v[178:179], off sc1
	v_mfma_f32_16x16x32_bf16 v[52:55], v[158:161], v[202:205], v[52:55]
	v_mfma_f32_16x16x32_bf16 v[48:51], v[158:161], v[206:209], v[48:51]
	s_add_u32 s50, s48, s16
	s_addc_u32 s51, s49, s17
	s_add_u32 m0, s61, 0x2000
	v_lshl_add_u64 v[178:179], v[130:131], 0, s[50:51]
	global_load_lds_dwordx4 v[178:179], off sc1
	v_mfma_f32_16x16x32_bf16 v[44:47], v[162:165], v[194:197], v[44:47]
	v_mfma_f32_16x16x32_bf16 v[32:35], v[162:165], v[198:201], v[32:35]
	s_add_u32 s50, s48, s18
	s_addc_u32 s51, s49, s19
	s_add_u32 m0, s61, 0x4000
	v_lshl_add_u64 v[178:179], v[130:131], 0, s[50:51]
	global_load_lds_dwordx4 v[178:179], off sc1
	v_mfma_f32_16x16x32_bf16 v[28:31], v[162:165], v[202:205], v[28:31]
	v_mfma_f32_16x16x32_bf16 v[24:27], v[162:165], v[206:209], v[24:27]
	s_add_u32 s50, s48, s22
	s_addc_u32 s51, s49, s23
	s_add_u32 m0, s61, 0x6000
	v_lshl_add_u64 v[178:179], v[130:131], 0, s[50:51]
	global_load_lds_dwordx4 v[178:179], off sc1
	v_mfma_f32_16x16x32_bf16 v[20:23], v[166:169], v[194:197], v[20:23]
	v_mfma_f32_16x16x32_bf16 v[16:19], v[166:169], v[198:201], v[16:19]
	s_add_u32 s50, s48, s36
	s_addc_u32 s51, s49, s37
	s_add_u32 m0, s61, 0x8000
	v_lshl_add_u64 v[178:179], v[132:133], 0, s[50:51]
	global_load_lds_dwordx4 v[178:179], off sc1
	v_mfma_f32_16x16x32_bf16 v[12:15], v[166:169], v[202:205], v[12:15]
	v_mfma_f32_16x16x32_bf16 v[8:11], v[166:169], v[206:209], v[8:11]
	s_add_u32 s50, s48, s40
	s_addc_u32 s51, s49, s41
	s_add_u32 m0, s61, 0xa000
	v_lshl_add_u64 v[178:179], v[132:133], 0, s[50:51]
	global_load_lds_dwordx4 v[178:179], off sc1
	v_mfma_f32_16x16x32_bf16 v[4:7], v[170:173], v[194:197], v[4:7]
	v_mfma_f32_16x16x32_bf16 v[0:3], v[170:173], v[198:201], v[0:3]
	s_add_u32 s50, s48, s42
	s_addc_u32 s51, s49, s43
	s_add_u32 m0, s61, 0xc000
	v_lshl_add_u64 v[178:179], v[132:133], 0, s[50:51]
	global_load_lds_dwordx4 v[178:179], off sc1
	v_mfma_f32_16x16x32_bf16 v[40:43], v[170:173], v[202:205], v[40:43]
	v_mfma_f32_16x16x32_bf16 v[36:39], v[170:173], v[206:209], v[36:39]
	s_add_u32 s50, s48, s44
	s_addc_u32 s51, s49, s45
	s_add_u32 m0, s61, 0xe000
	v_lshl_add_u64 v[178:179], v[132:133], 0, s[50:51]
	global_load_lds_dwordx4 v[178:179], off sc1

.LBB0_933:
	s_mul_hi_i32 s21, s70, 0x2e8ba2e9
	s_lshr_b32 s56, s21, 31
	s_ashr_i32 s71, s21, 4
	s_add_i32 s71, s71, s56
	s_and_b32 s20, s70, 7
	s_lshl_b32 s62, s71, 3
	s_or_b32 s58, s62, s20
	s_ashr_i32 s20, s70, 3
	s_mul_hi_i32 s21, s20, 0x2e8ba2e9
	v_mov_b32_e32 v6, v181
	s_lshr_b32 s56, s21, 31
	s_ashr_i32 s21, s21, 1
	s_add_i32 s21, s21, s56
	v_lshrrev_b32_e32 v7, 4, v6
	v_lshlrev_b32_e32 v1, 6, v6
	v_xor_b32_e32 v0, v7, v6
	v_and_b32_e32 v8, 0x3c0, v1
	v_lshlrev_b32_e32 v1, 7, v6
	s_mul_i32 s21, s21, 11
	s_ashr_i32 s59, s58, 31
	v_lshlrev_b32_e32 v0, 3, v0
	v_and_b32_e32 v1, 0xfffffc00, v1
	s_and_b32 s64, s69, 7
	s_sub_i32 s56, s20, s21
	s_lshl_b64 s[20:21], s[58:59], 19
	v_and_or_b32 v0, v0, 56, v1
	s_add_u32 s20, s3, s20
	v_ashrrev_i32_e32 v1, 31, v0
	s_addc_u32 s21, s66, s21
	v_lshlrev_b64 v[0:1], 1, v[0:1]
	v_lshl_add_u32 v130, v6, 4, 0
	v_lshl_add_u64 v[2:3], s[20:21], 0, v[0:1]
	v_readfirstlane_b32 s20, v130
	v_add_u32_e32 v9, 0x2000, v130
	s_mov_b32 m0, s20
	v_readfirstlane_b32 s20, v9
	v_add_u32_e32 v9, 0x4000, v130
	s_waitcnt vmcnt(63) expcnt(7) lgkmcnt(15)
	s_barrier
	global_load_lds_dwordx4 v[2:3], off
	v_lshl_add_u64 v[4:5], v[2:3], 0, s[14:15]
	s_mov_b32 m0, s20
	v_readfirstlane_b32 s20, v9
	global_load_lds_dwordx4 v[4:5], off
	v_lshl_add_u64 v[4:5], v[2:3], 0, s[16:17]
	s_mov_b32 m0, s20
	s_ashr_i32 s57, s56, 31
	global_load_lds_dwordx4 v[4:5], off
	v_add_u32_e32 v4, 0x6000, v130
	s_lshl_b64 s[60:61], s[56:57], 19
	v_readfirstlane_b32 s20, v4
	v_lshl_add_u64 v[2:3], v[2:3], 0, s[18:19]
	s_mov_b32 m0, s20
	s_add_u32 s60, s34, s60
	global_load_lds_dwordx4 v[2:3], off
	v_add_u32_e32 v2, 0x8000, v130
	s_addc_u32 s61, s35, s61
	v_readfirstlane_b32 s20, v2
	v_add_u32_e32 v4, 0xa000, v130
	v_lshl_add_u64 v[140:141], s[60:61], 0, v[0:1]
	s_mov_b32 m0, s20
	v_readfirstlane_b32 s20, v4
	v_add_u32_e32 v4, 0xc000, v130
	global_load_lds_dwordx4 v[140:141], off
	v_lshl_add_u64 v[2:3], v[140:141], 0, s[14:15]
	s_mov_b32 m0, s20
	v_readfirstlane_b32 s20, v4
	v_add_u32_e32 v4, 0xe000, v130
	global_load_lds_dwordx4 v[2:3], off
	v_lshl_add_u64 v[2:3], v[140:141], 0, s[16:17]
	s_mov_b32 m0, s20
	v_readfirstlane_b32 s20, v4
	global_load_lds_dwordx4 v[2:3], off
	v_lshl_add_u64 v[2:3], v[140:141], 0, s[18:19]
	s_mov_b32 m0, s20
	v_ashrrev_i32_e32 v4, 6, v6
	global_load_lds_dwordx4 v[2:3], off
	v_lshrrev_b32_e32 v5, 30, v4
	v_add_u32_e32 v5, v4, v5
	s_or_b32 s20, s62, s64
	v_bfe_u32 v2, v6, 4, 2
	v_bfe_u32 v3, v6, 1, 3
	v_and_b32_e32 v6, 0x7fffc, v5
	s_ashr_i32 s21, s20, 31
	v_sub_u32_e32 v4, v4, v6
	s_lshl_b64 s[20:21], s[20:21], 19
	v_lshlrev_b32_e32 v150, 13, v4
	v_bitop3_b32 v4, v7, v3, 3 bitop3:0x6c
	v_bitop3_b32 v2, v2, v3, 4 bitop3:0x36
	s_add_u32 s20, s34, s20
	v_lshlrev_b32_e32 v5, 12, v5
	v_lshlrev_b32_e32 v4, 3, v4
	v_lshlrev_b32_e32 v2, 3, v2
	s_addc_u32 s21, s35, s21
	v_and_b32_e32 v149, 0xffffc000, v5
	v_lshl_add_u64 v[142:143], s[20:21], 0, v[0:1]
	s_mov_b64 s[60:61], 0
	v_lshlrev_b32_e32 v151, 1, v8
	v_lshlrev_b32_e32 v152, 1, v4
	v_lshlrev_b32_e32 v153, 1, v2
	s_mov_b32 s59, 0
	s_mov_b32 s57, 0
	v_mov_b32_e32 v40, 0
	v_mov_b32_e32 v41, v131
	v_mov_b32_e32 v42, v131
	v_mov_b32_e32 v43, v131
	v_mov_b32_e32 v48, 0
	v_mov_b32_e32 v49, v131
	v_mov_b32_e32 v50, v131
	v_mov_b32_e32 v51, v131
	v_mov_b32_e32 v0, 0
	v_mov_b32_e32 v1, v131
	v_mov_b32_e32 v2, v131
	v_mov_b32_e32 v3, v131
	v_mov_b32_e32 v4, 0
	v_mov_b32_e32 v5, v131
	v_mov_b32_e32 v6, v131
	v_mov_b32_e32 v7, v131
	v_mov_b32_e32 v8, 0
	v_mov_b32_e32 v9, v131
	v_mov_b32_e32 v10, v131
	v_mov_b32_e32 v11, v131
	v_mov_b32_e32 v12, 0
	v_mov_b32_e32 v13, v131
	v_mov_b32_e32 v14, v131
	v_mov_b32_e32 v15, v131
	v_mov_b32_e32 v16, 0
	v_mov_b32_e32 v17, v131
	v_mov_b32_e32 v18, v131
	v_mov_b32_e32 v19, v131
	v_mov_b32_e32 v20, 0
	v_mov_b32_e32 v21, v131
	v_mov_b32_e32 v22, v131
	v_mov_b32_e32 v23, v131
	v_mov_b32_e32 v24, 0
	v_mov_b32_e32 v25, v131
	v_mov_b32_e32 v26, v131
	v_mov_b32_e32 v27, v131
	v_mov_b32_e32 v28, 0
	v_mov_b32_e32 v29, v131
	v_mov_b32_e32 v30, v131
	v_mov_b32_e32 v31, v131
	v_mov_b32_e32 v32, 0
	v_mov_b32_e32 v33, v131
	v_mov_b32_e32 v34, v131
	v_mov_b32_e32 v35, v131
	v_mov_b32_e32 v36, 0
	v_mov_b32_e32 v37, v131
	v_mov_b32_e32 v38, v131
	v_mov_b32_e32 v39, v131
	v_mov_b32_e32 v44, 0
	v_mov_b32_e32 v45, v131
	v_mov_b32_e32 v46, v131
	v_mov_b32_e32 v47, v131
	v_mov_b32_e32 v52, 0
	v_mov_b32_e32 v53, v131
	v_mov_b32_e32 v54, v131
	v_mov_b32_e32 v55, v131
	v_mov_b32_e32 v56, 0
	v_mov_b32_e32 v57, v131
	v_mov_b32_e32 v58, v131
	v_mov_b32_e32 v59, v131
	v_mov_b32_e32 v60, 0
	v_mov_b32_e32 v61, v131
	v_mov_b32_e32 v62, v131
	v_mov_b32_e32 v63, v131
	v_mov_b32_e32 v64, 0
	v_mov_b32_e32 v65, v131
	v_mov_b32_e32 v66, v131
	v_mov_b32_e32 v67, v131
	v_mov_b32_e32 v68, 0
	v_mov_b32_e32 v69, v131
	v_mov_b32_e32 v70, v131
	v_mov_b32_e32 v71, v131
	v_mov_b32_e32 v72, 0
	v_mov_b32_e32 v73, v131
	v_mov_b32_e32 v74, v131
	v_mov_b32_e32 v75, v131
	v_mov_b32_e32 v76, 0
	v_mov_b32_e32 v77, v131
	v_mov_b32_e32 v78, v131
	v_mov_b32_e32 v79, v131
	v_mov_b32_e32 v80, 0
	v_mov_b32_e32 v81, v131
	v_mov_b32_e32 v82, v131
	v_mov_b32_e32 v83, v131
	v_mov_b32_e32 v84, 0
	v_mov_b32_e32 v85, v131
	v_mov_b32_e32 v86, v131
	v_mov_b32_e32 v87, v131
	v_mov_b32_e32 v88, 0
	v_mov_b32_e32 v89, v131
	v_mov_b32_e32 v90, v131
	v_mov_b32_e32 v91, v131
	v_mov_b32_e32 v92, 0
	v_mov_b32_e32 v93, v131
	v_mov_b32_e32 v94, v131
	v_mov_b32_e32 v95, v131
	v_mov_b32_e32 v96, 0
	v_mov_b32_e32 v97, v131
	v_mov_b32_e32 v98, v131
	v_mov_b32_e32 v99, v131
	v_mov_b32_e32 v100, 0
	v_mov_b32_e32 v101, v131
	v_mov_b32_e32 v102, v131
	v_mov_b32_e32 v103, v131
	v_mov_b32_e32 v104, 0
	v_mov_b32_e32 v105, v131
	v_mov_b32_e32 v106, v131
	v_mov_b32_e32 v107, v131
	v_mov_b32_e32 v108, 0
	v_mov_b32_e32 v109, v131
	v_mov_b32_e32 v110, v131
	v_mov_b32_e32 v111, v131
	v_mov_b32_e32 v112, 0
	v_mov_b32_e32 v113, v131
	v_mov_b32_e32 v114, v131
	v_mov_b32_e32 v115, v131
	v_mov_b32_e32 v116, 0
	v_mov_b32_e32 v117, v131
	v_mov_b32_e32 v118, v131
	v_mov_b32_e32 v119, v131
	v_mov_b32_e32 v120, 0
	v_mov_b32_e32 v121, v131
	v_mov_b32_e32 v122, v131
	v_mov_b32_e32 v123, v131
	v_mov_b32_e32 v124, 0
	v_mov_b32_e32 v125, v131
	v_mov_b32_e32 v126, v131
	v_mov_b32_e32 v127, v131
	s_waitcnt vmcnt(0) lgkmcnt(0)
	s_barrier
	v_add3_u32 v180, v149, v151, v152
	v_add3_u32 v223, v150, v151, v152
	v_add3_u32 v222, v149, v151, v153
	v_add3_u32 v224, v150, v151, v153
	v_readfirstlane_b32 s59, v130
	ds_read_b128 v[154:157], v180
	ds_read_b128 v[158:161], v180 offset:2048
	ds_read_b128 v[162:165], v180 offset:4096
	ds_read_b128 v[166:169], v180 offset:6144
	ds_read_b128 v[190:193], v223 offset:32768
	ds_read_b128 v[194:197], v223 offset:34816
	ds_read_b128 v[198:201], v223 offset:36864
	ds_read_b128 v[202:205], v223 offset:38912
	s_mov_b32 s57, 0
	s_mov_b64 s[60:61], 0
	s_add_u32 s59, s59, 0x10000
	s_add_u32 s62, s60, s22
	s_addc_u32 s63, s61, s23
	s_mov_b32 m0, s59
	v_lshl_add_u64 v[178:179], v[142:143], 0, s[62:63]
	global_load_lds_dwordx4 v[178:179], off sc1
	s_add_u32 s62, s60, s36
	s_addc_u32 s63, s61, s37
	s_add_u32 m0, s59, 0x2000
	v_lshl_add_u64 v[178:179], v[142:143], 0, s[62:63]
	global_load_lds_dwordx4 v[178:179], off sc1
	s_add_u32 s62, s60, s38
	s_addc_u32 s63, s61, s39
	s_add_u32 m0, s59, 0x4000
	v_lshl_add_u64 v[178:179], v[142:143], 0, s[62:63]
	global_load_lds_dwordx4 v[178:179], off sc1
	s_add_u32 s62, s60, s40
	s_addc_u32 s63, s61, s41
	s_add_u32 m0, s59, 0x6000
	v_lshl_add_u64 v[178:179], v[142:143], 0, s[62:63]
	global_load_lds_dwordx4 v[178:179], off sc1
	s_add_u32 s62, s60, s42
	s_addc_u32 s63, s61, s43
	s_add_u32 m0, s59, 0x8000
	v_lshl_add_u64 v[178:179], v[140:141], 0, s[62:63]
	global_load_lds_dwordx4 v[178:179], off sc1
	s_add_u32 s62, s60, s44
	s_addc_u32 s63, s61, s45
	s_add_u32 m0, s59, 0xa000
	v_lshl_add_u64 v[178:179], v[140:141], 0, s[62:63]
	global_load_lds_dwordx4 v[178:179], off sc1
	s_add_u32 s62, s60, s46
	s_addc_u32 s63, s61, s47
	s_add_u32 m0, s59, 0xc000
	v_lshl_add_u64 v[178:179], v[140:141], 0, s[62:63]
	global_load_lds_dwordx4 v[178:179], off sc1
	s_add_u32 s62, s60, s48
	s_addc_u32 s63, s61, s49
	s_add_u32 m0, s59, 0xe000
	v_lshl_add_u64 v[178:179], v[140:141], 0, s[62:63]
	global_load_lds_dwordx4 v[178:179], off sc1
	s_branch .Lg8_entry
.Lg8_top:
	s_waitcnt lgkmcnt(0)
	s_waitcnt vmcnt(0)
	s_barrier
	v_xor_b32_e32 v180, 0x10000, v180
	v_xor_b32_e32 v223, 0x10000, v223
	v_xor_b32_e32 v222, 0x10000, v222
	v_xor_b32_e32 v224, 0x10000, v224
	s_xor_b32 s59, s59, 0x10000
	ds_read_b128 v[154:157], v180
	ds_read_b128 v[158:161], v180 offset:2048
	ds_read_b128 v[162:165], v180 offset:4096
	ds_read_b128 v[166:169], v180 offset:6144
	ds_read_b128 v[190:193], v223 offset:32768
	ds_read_b128 v[194:197], v223 offset:34816
	ds_read_b128 v[198:201], v223 offset:36864
	ds_read_b128 v[202:205], v223 offset:38912
	v_mfma_f32_16x16x32_bf16 v[60:63], v[170:173], v[206:209], v[60:63]
	v_mfma_f32_16x16x32_bf16 v[56:59], v[170:173], v[210:213], v[56:59]
	s_add_u32 s62, s60, s22
	s_addc_u32 s63, s61, s23
	s_mov_b32 m0, s59
	v_lshl_add_u64 v[178:179], v[142:143], 0, s[62:63]
	global_load_lds_dwordx4 v[178:179], off sc1
	v_mfma_f32_16x16x32_bf16 v[52:55], v[170:173], v[214:217], v[52:55]
	v_mfma_f32_16x16x32_bf16 v[44:47], v[170:173], v[218:221], v[44:47]
	s_add_u32 s62, s60, s36
	s_addc_u32 s63, s61, s37
	s_add_u32 m0, s59, 0x2000
	v_lshl_add_u64 v[178:179], v[142:143], 0, s[62:63]
	global_load_lds_dwordx4 v[178:179], off sc1
	v_mfma_f32_16x16x32_bf16 v[36:39], v[174:177], v[206:209], v[36:39]
	v_mfma_f32_16x16x32_bf16 v[32:35], v[174:177], v[210:213], v[32:35]
	s_add_u32 s62, s60, s38
	s_addc_u32 s63, s61, s39
	s_add_u32 m0, s59, 0x4000
	v_lshl_add_u64 v[178:179], v[142:143], 0, s[62:63]
	global_load_lds_dwordx4 v[178:179], off sc1
	v_mfma_f32_16x16x32_bf16 v[28:31], v[174:177], v[214:217], v[28:31]
	v_mfma_f32_16x16x32_bf16 v[24:27], v[174:177], v[218:221], v[24:27]
	s_add_u32 s62, s60, s40
	s_addc_u32 s63, s61, s41
	s_add_u32 m0, s59, 0x6000
	v_lshl_add_u64 v[178:179], v[142:143], 0, s[62:63]
	global_load_lds_dwordx4 v[178:179], off sc1
	v_mfma_f32_16x16x32_bf16 v[20:23], v[182:185], v[206:209], v[20:23]
	v_mfma_f32_16x16x32_bf16 v[16:19], v[182:185], v[210:213], v[16:19]
	s_add_u32 s62, s60, s42
	s_addc_u32 s63, s61, s43
	s_add_u32 m0, s59, 0x8000
	v_lshl_add_u64 v[178:179], v[140:141], 0, s[62:63]
	global_load_lds_dwordx4 v[178:179], off sc1
	v_mfma_f32_16x16x32_bf16 v[12:15], v[182:185], v[214:217], v[12:15]
	v_mfma_f32_16x16x32_bf16 v[8:11], v[182:185], v[218:221], v[8:11]
	s_add_u32 s62, s60, s44
	s_addc_u32 s63, s61, s45
	s_add_u32 m0, s59, 0xa000
	v_lshl_add_u64 v[178:179], v[140:141], 0, s[62:63]
	global_load_lds_dwordx4 v[178:179], off sc1
	v_mfma_f32_16x16x32_bf16 v[4:7], v[186:189], v[206:209], v[4:7]
	v_mfma_f32_16x16x32_bf16 v[0:3], v[186:189], v[210:213], v[0:3]
	s_add_u32 s62, s60, s46
	s_addc_u32 s63, s61, s47
	s_add_u32 m0, s59, 0xc000
	v_lshl_add_u64 v[178:179], v[140:141], 0, s[62:63]
	global_load_lds_dwordx4 v[178:179], off sc1
	v_mfma_f32_16x16x32_bf16 v[48:51], v[186:189], v[214:217], v[48:51]
	v_mfma_f32_16x16x32_bf16 v[40:43], v[186:189], v[218:221], v[40:43]
	s_add_u32 s62, s60, s48
	s_addc_u32 s63, s61, s49
	s_add_u32 m0, s59, 0xe000
	v_lshl_add_u64 v[178:179], v[140:141], 0, s[62:63]
	global_load_lds_dwordx4 v[178:179], off sc1

.LBB0_1331:
	s_ashr_i32 s20, s58, 2
	v_mov_b32_e32 v6, v181
	s_and_b32 s4, s58, 7
	s_and_b32 s47, s20, -8
	s_or_b32 s42, s47, s4
	v_lshrrev_b32_e32 v7, 4, v6
	v_lshlrev_b32_e32 v1, 6, v6
	v_xor_b32_e32 v0, v7, v6
	v_and_b32_e32 v8, 0x3c0, v1
	v_lshlrev_b32_e32 v1, 8, v6
	s_ashr_i32 s43, s42, 31
	v_lshlrev_b32_e32 v0, 3, v0
	v_and_b32_e32 v1, 0xfffff800, v1
	s_and_b32 s46, s57, 7
	s_bfe_u32 s4, s58, 0x20003
	s_lshl_b64 s[20:21], s[42:43], 20
	v_and_or_b32 v0, v0, 56, v1
	s_add_u32 s20, s3, s20
	v_ashrrev_i32_e32 v1, 31, v0
	s_addc_u32 s21, s48, s21
	v_lshlrev_b64 v[0:1], 1, v[0:1]
	v_lshl_add_u32 v134, v6, 4, 0
	v_lshl_add_u64 v[2:3], s[20:21], 0, v[0:1]
	v_readfirstlane_b32 s20, v134
	v_add_u32_e32 v9, 0x2000, v134
	s_mov_b32 m0, s20
	v_readfirstlane_b32 s20, v9
	v_add_u32_e32 v9, 0x4000, v134
	s_waitcnt vmcnt(63) expcnt(7) lgkmcnt(15)
	s_barrier
	global_load_lds_dwordx4 v[2:3], off
	v_lshl_add_u64 v[4:5], v[2:3], 0, s[6:7]
	s_mov_b32 m0, s20
	v_readfirstlane_b32 s20, v9
	global_load_lds_dwordx4 v[4:5], off
	v_lshl_add_u64 v[4:5], v[2:3], 0, s[8:9]
	s_mov_b32 m0, s20
	s_lshl_b32 s43, s4, 20
	global_load_lds_dwordx4 v[4:5], off
	v_add_u32_e32 v4, 0x6000, v134
	s_add_u32 s44, s49, s43
	v_readfirstlane_b32 s20, v4
	v_add_u32_e32 v4, 0x8000, v134
	s_addc_u32 s45, s56, 0
	v_lshl_add_u64 v[2:3], v[2:3], 0, s[10:11]
	s_mov_b32 m0, s20
	v_readfirstlane_b32 s20, v4
	v_add_u32_e32 v9, 0xa000, v134
	global_load_lds_dwordx4 v[2:3], off
	v_lshl_add_u64 v[2:3], s[44:45], 0, v[0:1]
	s_mov_b32 m0, s20
	v_readfirstlane_b32 s20, v9
	v_add_u32_e32 v9, 0xc000, v134
	global_load_lds_dwordx4 v[2:3], off
	v_lshl_add_u64 v[4:5], v[2:3], 0, s[6:7]
	s_mov_b32 m0, s20
	v_readfirstlane_b32 s20, v9
	global_load_lds_dwordx4 v[4:5], off
	v_lshl_add_u64 v[4:5], v[2:3], 0, s[8:9]
	s_mov_b32 m0, s20
	v_lshl_add_u64 v[2:3], v[2:3], 0, s[10:11]
	global_load_lds_dwordx4 v[4:5], off
	v_add_u32_e32 v4, 0xe000, v134
	v_mov_b32_e32 v36, 0
	v_readfirstlane_b32 s20, v4
	s_mov_b32 m0, s20
	v_ashrrev_i32_e32 v4, 6, v6
	global_load_lds_dwordx4 v[2:3], off
	s_or_b32 s20, s47, s46
	v_lshrrev_b32_e32 v5, 30, v4
	s_ashr_i32 s21, s20, 31
	v_add_u32_e32 v5, v4, v5
	s_lshl_b64 s[20:21], s[20:21], 20
	v_bfe_u32 v2, v6, 4, 2
	v_bfe_u32 v3, v6, 1, 3
	v_and_b32_e32 v6, 0x7fffc, v5
	s_add_u32 s20, s34, s20
	v_sub_u32_e32 v4, v4, v6
	s_addc_u32 s21, s35, s21
	v_lshlrev_b32_e32 v136, 13, v4
	v_bitop3_b32 v4, v7, v3, 3 bitop3:0x6c
	v_bitop3_b32 v2, v2, v3, 4 bitop3:0x36
	v_lshl_add_u64 v[130:131], s[20:21], 0, v[0:1]
	s_add_u32 s20, s34, s43
	v_lshlrev_b32_e32 v5, 12, v5
	v_lshlrev_b32_e32 v4, 3, v4
	v_lshlrev_b32_e32 v2, 3, v2
	s_addc_u32 s21, s35, 0
	v_and_b32_e32 v135, 0xffffc000, v5
	v_lshl_add_u64 v[132:133], s[20:21], 0, v[0:1]
	s_mov_b64 s[44:45], 0
	v_lshlrev_b32_e32 v137, 1, v8
	v_lshlrev_b32_e32 v138, 1, v4
	v_lshlrev_b32_e32 v139, 1, v2
	s_mov_b32 s59, 0
	s_mov_b32 s43, 0
	v_mov_b32_e32 v37, v36
	v_mov_b32_e32 v38, v36
	v_mov_b32_e32 v39, v36
	v_mov_b32_e32 v40, v36
	v_mov_b32_e32 v41, v36
	v_mov_b32_e32 v42, v36
	v_mov_b32_e32 v43, v36
	v_mov_b32_e32 v0, v36
	v_mov_b32_e32 v1, v36
	v_mov_b32_e32 v2, v36
	v_mov_b32_e32 v3, v36
	v_mov_b32_e32 v4, v36
	v_mov_b32_e32 v5, v36
	v_mov_b32_e32 v6, v36
	v_mov_b32_e32 v7, v36
	v_mov_b32_e32 v8, v36
	v_mov_b32_e32 v9, v36
	v_mov_b32_e32 v10, v36
	v_mov_b32_e32 v11, v36
	v_mov_b32_e32 v12, v36
	v_mov_b32_e32 v13, v36
	v_mov_b32_e32 v14, v36
	v_mov_b32_e32 v15, v36
	v_mov_b32_e32 v16, v36
	v_mov_b32_e32 v17, v36
	v_mov_b32_e32 v18, v36
	v_mov_b32_e32 v19, v36
	v_mov_b32_e32 v20, v36
	v_mov_b32_e32 v21, v36
	v_mov_b32_e32 v22, v36
	v_mov_b32_e32 v23, v36
	v_mov_b32_e32 v24, v36
	v_mov_b32_e32 v25, v36
	v_mov_b32_e32 v26, v36
	v_mov_b32_e32 v27, v36
	v_mov_b32_e32 v28, v36
	v_mov_b32_e32 v29, v36
	v_mov_b32_e32 v30, v36
	v_mov_b32_e32 v31, v36
	v_mov_b32_e32 v32, v36
	v_mov_b32_e32 v33, v36
	v_mov_b32_e32 v34, v36
	v_mov_b32_e32 v35, v36
	v_mov_b32_e32 v44, v36
	v_mov_b32_e32 v45, v36
	v_mov_b32_e32 v46, v36
	v_mov_b32_e32 v47, v36
	v_mov_b32_e32 v48, v36
	v_mov_b32_e32 v49, v36
	v_mov_b32_e32 v50, v36
	v_mov_b32_e32 v51, v36
	v_mov_b32_e32 v52, v36
	v_mov_b32_e32 v53, v36
	v_mov_b32_e32 v54, v36
	v_mov_b32_e32 v55, v36
	v_mov_b32_e32 v56, v36
	v_mov_b32_e32 v57, v36
	v_mov_b32_e32 v58, v36
	v_mov_b32_e32 v59, v36
	v_mov_b32_e32 v60, v36
	v_mov_b32_e32 v61, v36
	v_mov_b32_e32 v62, v36
	v_mov_b32_e32 v63, v36
	v_mov_b32_e32 v64, v36
	v_mov_b32_e32 v65, v36
	v_mov_b32_e32 v66, v36
	v_mov_b32_e32 v67, v36
	v_mov_b32_e32 v68, v36
	v_mov_b32_e32 v69, v36
	v_mov_b32_e32 v70, v36
	v_mov_b32_e32 v71, v36
	v_mov_b32_e32 v72, v36
	v_mov_b32_e32 v73, v36
	v_mov_b32_e32 v74, v36
	v_mov_b32_e32 v75, v36
	v_mov_b32_e32 v76, v36
	v_mov_b32_e32 v77, v36
	v_mov_b32_e32 v78, v36
	v_mov_b32_e32 v79, v36
	v_mov_b32_e32 v80, v36
	v_mov_b32_e32 v81, v36
	v_mov_b32_e32 v82, v36
	v_mov_b32_e32 v83, v36
	v_mov_b32_e32 v84, v36
	v_mov_b32_e32 v85, v36
	v_mov_b32_e32 v86, v36
	v_mov_b32_e32 v87, v36
	v_mov_b32_e32 v88, v36
	v_mov_b32_e32 v89, v36
	v_mov_b32_e32 v90, v36
	v_mov_b32_e32 v91, v36
	v_mov_b32_e32 v92, v36
	v_mov_b32_e32 v93, v36
	v_mov_b32_e32 v94, v36
	v_mov_b32_e32 v95, v36
	v_mov_b32_e32 v96, v36
	v_mov_b32_e32 v97, v36
	v_mov_b32_e32 v98, v36
	v_mov_b32_e32 v99, v36
	v_mov_b32_e32 v100, v36
	v_mov_b32_e32 v101, v36
	v_mov_b32_e32 v102, v36
	v_mov_b32_e32 v103, v36
	v_mov_b32_e32 v104, v36
	v_mov_b32_e32 v105, v36
	v_mov_b32_e32 v106, v36
	v_mov_b32_e32 v107, v36
	v_mov_b32_e32 v108, v36
	v_mov_b32_e32 v109, v36
	v_mov_b32_e32 v110, v36
	v_mov_b32_e32 v111, v36
	v_mov_b32_e32 v112, v36
	v_mov_b32_e32 v113, v36
	v_mov_b32_e32 v114, v36
	v_mov_b32_e32 v115, v36
	v_mov_b32_e32 v116, v36
	v_mov_b32_e32 v117, v36
	v_mov_b32_e32 v118, v36
	v_mov_b32_e32 v119, v36
	v_mov_b32_e32 v120, v36
	v_mov_b32_e32 v121, v36
	v_mov_b32_e32 v122, v36
	v_mov_b32_e32 v123, v36
	v_mov_b32_e32 v124, v36
	v_mov_b32_e32 v125, v36
	v_mov_b32_e32 v126, v36
	v_mov_b32_e32 v127, v36
	s_waitcnt vmcnt(0) lgkmcnt(0)
	s_barrier
	v_add3_u32 v141, v135, v137, v138
	v_add3_u32 v210, v136, v137, v138
	v_add3_u32 v180, v135, v137, v139
	v_add3_u32 v211, v136, v137, v139
	v_readfirstlane_b32 s59, v134
	ds_read_b128 v[142:145], v141
	ds_read_b128 v[146:149], v141 offset:2048
	ds_read_b128 v[150:153], v141 offset:4096
	ds_read_b128 v[154:157], v141 offset:6144
	ds_read_b128 v[174:177], v210 offset:32768
	ds_read_b128 v[182:185], v210 offset:34816
	ds_read_b128 v[186:189], v210 offset:36864
	ds_read_b128 v[190:193], v210 offset:38912
	s_mov_b32 s43, 0
	s_mov_b64 s[44:45], 0
	s_add_u32 s59, s59, 0x10000
	s_add_u32 s46, s44, s12
	s_addc_u32 s47, s45, s13
	s_mov_b32 m0, s59
	v_lshl_add_u64 v[178:179], v[130:131], 0, s[46:47]
	global_load_lds_dwordx4 v[178:179], off sc1
	s_add_u32 s46, s44, s14
	s_addc_u32 s47, s45, s15
	s_add_u32 m0, s59, 0x2000
	v_lshl_add_u64 v[178:179], v[130:131], 0, s[46:47]
	global_load_lds_dwordx4 v[178:179], off sc1
	s_add_u32 s46, s44, s16
	s_addc_u32 s47, s45, s17
	s_add_u32 m0, s59, 0x4000
	v_lshl_add_u64 v[178:179], v[130:131], 0, s[46:47]
	global_load_lds_dwordx4 v[178:179], off sc1
	s_add_u32 s46, s44, s18
	s_addc_u32 s47, s45, s19
	s_add_u32 m0, s59, 0x6000
	v_lshl_add_u64 v[178:179], v[130:131], 0, s[46:47]
	global_load_lds_dwordx4 v[178:179], off sc1
	s_add_u32 s46, s44, s22
	s_addc_u32 s47, s45, s23
	s_add_u32 m0, s59, 0x8000
	v_lshl_add_u64 v[178:179], v[132:133], 0, s[46:47]
	global_load_lds_dwordx4 v[178:179], off sc1
	s_add_u32 s46, s44, s36
	s_addc_u32 s47, s45, s37
	s_add_u32 m0, s59, 0xa000
	v_lshl_add_u64 v[178:179], v[132:133], 0, s[46:47]
	global_load_lds_dwordx4 v[178:179], off sc1
	s_add_u32 s46, s44, s38
	s_addc_u32 s47, s45, s39
	s_add_u32 m0, s59, 0xc000
	v_lshl_add_u64 v[178:179], v[132:133], 0, s[46:47]
	global_load_lds_dwordx4 v[178:179], off sc1
	s_add_u32 s46, s44, s40
	s_addc_u32 s47, s45, s41
	s_add_u32 m0, s59, 0xe000
	v_lshl_add_u64 v[178:179], v[132:133], 0, s[46:47]
	global_load_lds_dwordx4 v[178:179], off sc1
	s_branch .Lg9_entry
.Lg9_top:
	s_waitcnt lgkmcnt(0)
	s_waitcnt vmcnt(0)
	s_barrier
	v_xor_b32_e32 v141, 0x10000, v141
	v_xor_b32_e32 v210, 0x10000, v210
	v_xor_b32_e32 v180, 0x10000, v180
	v_xor_b32_e32 v211, 0x10000, v211
	s_xor_b32 s59, s59, 0x10000
	ds_read_b128 v[142:145], v141
	ds_read_b128 v[146:149], v141 offset:2048
	ds_read_b128 v[150:153], v141 offset:4096
	ds_read_b128 v[154:157], v141 offset:6144
	ds_read_b128 v[174:177], v210 offset:32768
	ds_read_b128 v[182:185], v210 offset:34816
	ds_read_b128 v[186:189], v210 offset:36864
	ds_read_b128 v[190:193], v210 offset:38912
	v_mfma_f32_16x16x32_bf16 v[60:63], v[158:161], v[194:197], v[60:63]
	v_mfma_f32_16x16x32_bf16 v[56:59], v[158:161], v[198:201], v[56:59]
	s_add_u32 s46, s44, s12
	s_addc_u32 s47, s45, s13
	s_mov_b32 m0, s59
	v_lshl_add_u64 v[178:179], v[130:131], 0, s[46:47]
	global_load_lds_dwordx4 v[178:179], off sc1
	v_mfma_f32_16x16x32_bf16 v[52:55], v[158:161], v[202:205], v[52:55]
	v_mfma_f32_16x16x32_bf16 v[48:51], v[158:161], v[206:209], v[48:51]
	s_add_u32 s46, s44, s14
	s_addc_u32 s47, s45, s15
	s_add_u32 m0, s59, 0x2000
	v_lshl_add_u64 v[178:179], v[130:131], 0, s[46:47]
	global_load_lds_dwordx4 v[178:179], off sc1
	v_mfma_f32_16x16x32_bf16 v[44:47], v[162:165], v[194:197], v[44:47]
	v_mfma_f32_16x16x32_bf16 v[32:35], v[162:165], v[198:201], v[32:35]
	s_add_u32 s46, s44, s16
	s_addc_u32 s47, s45, s17
	s_add_u32 m0, s59, 0x4000
	v_lshl_add_u64 v[178:179], v[130:131], 0, s[46:47]
	global_load_lds_dwordx4 v[178:179], off sc1
	v_mfma_f32_16x16x32_bf16 v[28:31], v[162:165], v[202:205], v[28:31]
	v_mfma_f32_16x16x32_bf16 v[24:27], v[162:165], v[206:209], v[24:27]
	s_add_u32 s46, s44, s18
	s_addc_u32 s47, s45, s19
	s_add_u32 m0, s59, 0x6000
	v_lshl_add_u64 v[178:179], v[130:131], 0, s[46:47]
	global_load_lds_dwordx4 v[178:179], off sc1
	v_mfma_f32_16x16x32_bf16 v[20:23], v[166:169], v[194:197], v[20:23]
	v_mfma_f32_16x16x32_bf16 v[16:19], v[166:169], v[198:201], v[16:19]
	s_add_u32 s46, s44, s22
	s_addc_u32 s47, s45, s23
	s_add_u32 m0, s59, 0x8000
	v_lshl_add_u64 v[178:179], v[132:133], 0, s[46:47]
	global_load_lds_dwordx4 v[178:179], off sc1
	v_mfma_f32_16x16x32_bf16 v[12:15], v[166:169], v[202:205], v[12:15]
	v_mfma_f32_16x16x32_bf16 v[8:11], v[166:169], v[206:209], v[8:11]
	s_add_u32 s46, s44, s36
	s_addc_u32 s47, s45, s37
	s_add_u32 m0, s59, 0xa000
	v_lshl_add_u64 v[178:179], v[132:133], 0, s[46:47]
	global_load_lds_dwordx4 v[178:179], off sc1
	v_mfma_f32_16x16x32_bf16 v[4:7], v[170:173], v[194:197], v[4:7]
	v_mfma_f32_16x16x32_bf16 v[0:3], v[170:173], v[198:201], v[0:3]
	s_add_u32 s46, s44, s38
	s_addc_u32 s47, s45, s39
	s_add_u32 m0, s59, 0xc000
	v_lshl_add_u64 v[178:179], v[132:133], 0, s[46:47]
	global_load_lds_dwordx4 v[178:179], off sc1
	v_mfma_f32_16x16x32_bf16 v[40:43], v[170:173], v[202:205], v[40:43]
	v_mfma_f32_16x16x32_bf16 v[36:39], v[170:173], v[206:209], v[36:39]
	s_add_u32 s46, s44, s40
	s_addc_u32 s47, s45, s41
	s_add_u32 m0, s59, 0xe000
	v_lshl_add_u64 v[178:179], v[132:133], 0, s[46:47]
	global_load_lds_dwordx4 v[178:179], off sc1

.LBB0_1488:
	v_mov_b32_e32 v6, v181
	s_ashr_i32 s51, s50, 6
	v_lshrrev_b32_e32 v7, 4, v6
	v_lshlrev_b32_e32 v1, 6, v6
	v_xor_b32_e32 v0, v7, v6
	v_and_b32_e32 v8, 0x3c0, v1
	v_lshlrev_b32_e32 v1, 7, v6
	s_bfe_u32 s52, s50, 0x20006
	s_and_b32 s56, s49, 63
	s_and_b32 s53, s50, 63
	s_and_b32 s20, s51, -4
	v_lshlrev_b32_e32 v0, 3, v0
	v_and_b32_e32 v1, 0xfffffc00, v1
	s_lshl_b32 s46, s56, 19
	s_or_b32 s42, s20, s52
	s_lshl_b32 s20, s53, 19
	v_and_or_b32 v0, v0, 56, v1
	s_add_u32 s20, s3, s20
	v_ashrrev_i32_e32 v1, 31, v0
	s_addc_u32 s21, s48, 0
	v_lshlrev_b64 v[0:1], 1, v[0:1]
	v_lshl_add_u32 v129, v6, 4, 0
	v_lshl_add_u64 v[2:3], s[20:21], 0, v[0:1]
	v_readfirstlane_b32 s20, v129
	v_add_u32_e32 v9, 0x2000, v129
	s_mov_b32 m0, s20
	v_readfirstlane_b32 s20, v9
	v_add_u32_e32 v9, 0x4000, v129
	s_waitcnt vmcnt(63) expcnt(7) lgkmcnt(15)
	s_barrier
	global_load_lds_dwordx4 v[2:3], off
	v_lshl_add_u64 v[4:5], v[2:3], 0, s[8:9]
	s_mov_b32 m0, s20
	v_readfirstlane_b32 s20, v9
	global_load_lds_dwordx4 v[4:5], off
	v_lshl_add_u64 v[4:5], v[2:3], 0, s[10:11]
	s_mov_b32 m0, s20
	s_ashr_i32 s43, s42, 31
	global_load_lds_dwordx4 v[4:5], off
	v_add_u32_e32 v4, 0x6000, v129
	s_lshl_b64 s[44:45], s[42:43], 19
	v_readfirstlane_b32 s20, v4
	v_lshl_add_u64 v[2:3], v[2:3], 0, s[12:13]
	s_mov_b32 m0, s20
	s_add_u32 s44, s34, s44
	global_load_lds_dwordx4 v[2:3], off
	v_add_u32_e32 v2, 0x8000, v129
	s_addc_u32 s45, s35, s45
	v_readfirstlane_b32 s20, v2
	v_add_u32_e32 v4, 0xa000, v129
	v_lshl_add_u64 v[134:135], s[44:45], 0, v[0:1]
	s_mov_b32 m0, s20
	v_readfirstlane_b32 s20, v4
	v_add_u32_e32 v4, 0xc000, v129
	global_load_lds_dwordx4 v[134:135], off
	v_lshl_add_u64 v[2:3], v[134:135], 0, s[8:9]
	s_mov_b32 m0, s20
	v_readfirstlane_b32 s20, v4
	v_add_u32_e32 v4, 0xe000, v129
	global_load_lds_dwordx4 v[2:3], off
	v_lshl_add_u64 v[2:3], v[134:135], 0, s[10:11]
	s_mov_b32 m0, s20
	v_readfirstlane_b32 s20, v4
	global_load_lds_dwordx4 v[2:3], off
	v_lshl_add_u64 v[2:3], v[134:135], 0, s[12:13]
	s_mov_b32 m0, s20
	v_ashrrev_i32_e32 v4, 6, v6
	global_load_lds_dwordx4 v[2:3], off
	v_lshrrev_b32_e32 v5, 30, v4
	v_add_u32_e32 v5, v4, v5
	v_bfe_u32 v2, v6, 4, 2
	v_bfe_u32 v3, v6, 1, 3
	v_and_b32_e32 v6, 0x7fffc, v5
	v_sub_u32_e32 v4, v4, v6
	v_lshlrev_b32_e32 v139, 13, v4
	v_bitop3_b32 v4, v7, v3, 3 bitop3:0x6c
	v_bitop3_b32 v2, v2, v3, 4 bitop3:0x36
	s_add_u32 s20, s34, s46
	v_lshlrev_b32_e32 v5, 12, v5
	v_lshlrev_b32_e32 v4, 3, v4
	v_lshlrev_b32_e32 v2, 3, v2
	s_addc_u32 s21, s35, 0
	v_and_b32_e32 v138, 0xffffc000, v5
	v_lshl_add_u64 v[136:137], s[20:21], 0, v[0:1]
	s_mov_b64 s[44:45], 0
	s_waitcnt lgkmcnt(0)
	v_lshlrev_b32_e32 v140, 1, v8
	v_lshlrev_b32_e32 v141, 1, v4
	v_lshlrev_b32_e32 v142, 1, v2
	s_mov_b32 s57, 0
	s_mov_b32 s43, 0
	v_mov_b32_e32 v8, v128
	v_mov_b32_e32 v9, v128
	v_mov_b32_e32 v10, v128
	v_mov_b32_e32 v11, v128
	v_mov_b32_e32 v20, v128
	v_mov_b32_e32 v21, v128
	v_mov_b32_e32 v22, v128
	v_mov_b32_e32 v23, v128
	v_mov_b32_e32 v0, v128
	v_mov_b32_e32 v1, v128
	v_mov_b32_e32 v2, v128
	v_mov_b32_e32 v3, v128
	v_mov_b32_e32 v4, v128
	v_mov_b32_e32 v5, v128
	v_mov_b32_e32 v6, v128
	v_mov_b32_e32 v7, v128
	v_mov_b32_e32 v12, v128
	v_mov_b32_e32 v13, v128
	v_mov_b32_e32 v14, v128
	v_mov_b32_e32 v15, v128
	v_mov_b32_e32 v24, v128
	v_mov_b32_e32 v25, v128
	v_mov_b32_e32 v26, v128
	v_mov_b32_e32 v27, v128
	v_mov_b32_e32 v16, v128
	v_mov_b32_e32 v17, v128
	v_mov_b32_e32 v18, v128
	v_mov_b32_e32 v19, v128
	v_mov_b32_e32 v28, v128
	v_mov_b32_e32 v29, v128
	v_mov_b32_e32 v30, v128
	v_mov_b32_e32 v31, v128
	v_mov_b32_e32 v32, v128
	v_mov_b32_e32 v33, v128
	v_mov_b32_e32 v34, v128
	v_mov_b32_e32 v35, v128
	v_mov_b32_e32 v40, v128
	v_mov_b32_e32 v41, v128
	v_mov_b32_e32 v42, v128
	v_mov_b32_e32 v43, v128
	v_mov_b32_e32 v36, v128
	v_mov_b32_e32 v37, v128
	v_mov_b32_e32 v38, v128
	v_mov_b32_e32 v39, v128
	v_mov_b32_e32 v44, v128
	v_mov_b32_e32 v45, v128
	v_mov_b32_e32 v46, v128
	v_mov_b32_e32 v47, v128
	v_mov_b32_e32 v48, v128
	v_mov_b32_e32 v49, v128
	v_mov_b32_e32 v50, v128
	v_mov_b32_e32 v51, v128
	v_mov_b32_e32 v56, v128
	v_mov_b32_e32 v57, v128
	v_mov_b32_e32 v58, v128
	v_mov_b32_e32 v59, v128
	v_mov_b32_e32 v52, v128
	v_mov_b32_e32 v53, v128
	v_mov_b32_e32 v54, v128
	v_mov_b32_e32 v55, v128
	v_mov_b32_e32 v60, v128
	v_mov_b32_e32 v61, v128
	v_mov_b32_e32 v62, v128
	v_mov_b32_e32 v63, v128
	v_mov_b32_e32 v64, v128
	v_mov_b32_e32 v65, v128
	v_mov_b32_e32 v66, v128
	v_mov_b32_e32 v67, v128
	v_mov_b32_e32 v72, v128
	v_mov_b32_e32 v73, v128
	v_mov_b32_e32 v74, v128
	v_mov_b32_e32 v75, v128
	v_mov_b32_e32 v68, v128
	v_mov_b32_e32 v69, v128
	v_mov_b32_e32 v70, v128
	v_mov_b32_e32 v71, v128
	v_mov_b32_e32 v76, v128
	v_mov_b32_e32 v77, v128
	v_mov_b32_e32 v78, v128
	v_mov_b32_e32 v79, v128
	v_mov_b32_e32 v80, v128
	v_mov_b32_e32 v81, v128
	v_mov_b32_e32 v82, v128
	v_mov_b32_e32 v83, v128
	v_mov_b32_e32 v88, v128
	v_mov_b32_e32 v89, v128
	v_mov_b32_e32 v90, v128
	v_mov_b32_e32 v91, v128
	v_mov_b32_e32 v84, v128
	v_mov_b32_e32 v85, v128
	v_mov_b32_e32 v86, v128
	v_mov_b32_e32 v87, v128
	v_mov_b32_e32 v92, v128
	v_mov_b32_e32 v93, v128
	v_mov_b32_e32 v94, v128
	v_mov_b32_e32 v95, v128
	v_mov_b32_e32 v96, v128
	v_mov_b32_e32 v97, v128
	v_mov_b32_e32 v98, v128
	v_mov_b32_e32 v99, v128
	v_mov_b32_e32 v104, v128
	v_mov_b32_e32 v105, v128
	v_mov_b32_e32 v106, v128
	v_mov_b32_e32 v107, v128
	v_mov_b32_e32 v100, v128
	v_mov_b32_e32 v101, v128
	v_mov_b32_e32 v102, v128
	v_mov_b32_e32 v103, v128
	v_mov_b32_e32 v108, v128
	v_mov_b32_e32 v109, v128
	v_mov_b32_e32 v110, v128
	v_mov_b32_e32 v111, v128
	v_mov_b32_e32 v112, v128
	v_mov_b32_e32 v113, v128
	v_mov_b32_e32 v114, v128
	v_mov_b32_e32 v115, v128
	v_mov_b32_e32 v120, v128
	v_mov_b32_e32 v121, v128
	v_mov_b32_e32 v122, v128
	v_mov_b32_e32 v123, v128
	v_mov_b32_e32 v116, v128
	v_mov_b32_e32 v117, v128
	v_mov_b32_e32 v118, v128
	v_mov_b32_e32 v119, v128
	v_mov_b32_e32 v124, v128
	v_mov_b32_e32 v125, v128
	v_mov_b32_e32 v126, v128
	v_mov_b32_e32 v127, v128
	s_waitcnt vmcnt(0) lgkmcnt(0)
	s_barrier
	v_add3_u32 v143, v138, v140, v141
	v_add3_u32 v180, v139, v140, v141
	v_add3_u32 v155, v138, v140, v142
	v_add3_u32 v222, v139, v140, v142
	v_readfirstlane_b32 s57, v129
	ds_read_b128 v[156:159], v143
	ds_read_b128 v[160:163], v143 offset:2048
	ds_read_b128 v[164:167], v143 offset:4096
	ds_read_b128 v[168:171], v143 offset:6144
	ds_read_b128 v[190:193], v180 offset:32768
	ds_read_b128 v[194:197], v180 offset:34816
	ds_read_b128 v[198:201], v180 offset:36864
	ds_read_b128 v[202:205], v180 offset:38912
	s_mov_b32 s43, 0
	s_mov_b64 s[44:45], 0
	s_add_u32 s57, s57, 0x10000
	s_add_u32 s46, s44, s14
	s_addc_u32 s47, s45, s15
	s_mov_b32 m0, s57
	v_lshl_add_u64 v[144:145], v[136:137], 0, s[46:47]
	global_load_lds_dwordx4 v[144:145], off sc1
	s_add_u32 s46, s44, s16
	s_addc_u32 s47, s45, s17
	s_add_u32 m0, s57, 0x2000
	v_lshl_add_u64 v[144:145], v[136:137], 0, s[46:47]
	global_load_lds_dwordx4 v[144:145], off sc1
	s_add_u32 s46, s44, s18
	s_addc_u32 s47, s45, s19
	s_add_u32 m0, s57, 0x4000
	v_lshl_add_u64 v[144:145], v[136:137], 0, s[46:47]
	global_load_lds_dwordx4 v[144:145], off sc1
	s_add_u32 s46, s44, s22
	s_addc_u32 s47, s45, s23
	s_add_u32 m0, s57, 0x6000
	v_lshl_add_u64 v[144:145], v[136:137], 0, s[46:47]
	global_load_lds_dwordx4 v[144:145], off sc1
	s_add_u32 s46, s44, s30
	s_addc_u32 s47, s45, s31
	s_add_u32 m0, s57, 0x8000
	v_lshl_add_u64 v[144:145], v[134:135], 0, s[46:47]
	global_load_lds_dwordx4 v[144:145], off sc1
	s_add_u32 s46, s44, s36
	s_addc_u32 s47, s45, s37
	s_add_u32 m0, s57, 0xa000
	v_lshl_add_u64 v[144:145], v[134:135], 0, s[46:47]
	global_load_lds_dwordx4 v[144:145], off sc1
	s_add_u32 s46, s44, s38
	s_addc_u32 s47, s45, s39
	s_add_u32 m0, s57, 0xc000
	v_lshl_add_u64 v[144:145], v[134:135], 0, s[46:47]
	global_load_lds_dwordx4 v[144:145], off sc1
	s_add_u32 s46, s44, s40
	s_addc_u32 s47, s45, s41
	s_add_u32 m0, s57, 0xe000
	v_lshl_add_u64 v[144:145], v[134:135], 0, s[46:47]
	global_load_lds_dwordx4 v[144:145], off sc1
	s_branch .Lg10_entry
.Lg10_top:
	s_waitcnt lgkmcnt(0)
	s_waitcnt vmcnt(0)
	s_barrier
	v_xor_b32_e32 v143, 0x10000, v143
	v_xor_b32_e32 v180, 0x10000, v180
	v_xor_b32_e32 v155, 0x10000, v155
	v_xor_b32_e32 v222, 0x10000, v222
	s_xor_b32 s57, s57, 0x10000
	ds_read_b128 v[156:159], v143
	ds_read_b128 v[160:163], v143 offset:2048
	ds_read_b128 v[164:167], v143 offset:4096
	ds_read_b128 v[168:171], v143 offset:6144
	ds_read_b128 v[190:193], v180 offset:32768
	ds_read_b128 v[194:197], v180 offset:34816
	ds_read_b128 v[198:201], v180 offset:36864
	ds_read_b128 v[202:205], v180 offset:38912
	v_mfma_f32_16x16x32_bf16 v[60:63], v[172:175], v[206:209], v[60:63]
	v_mfma_f32_16x16x32_bf16 v[52:55], v[172:175], v[210:213], v[52:55]
	s_add_u32 s46, s44, s14
	s_addc_u32 s47, s45, s15
	s_mov_b32 m0, s57
	v_lshl_add_u64 v[144:145], v[136:137], 0, s[46:47]
	global_load_lds_dwordx4 v[144:145], off sc1
	v_mfma_f32_16x16x32_bf16 v[56:59], v[172:175], v[214:217], v[56:59]
	v_mfma_f32_16x16x32_bf16 v[48:51], v[172:175], v[218:221], v[48:51]
	s_add_u32 s46, s44, s16
	s_addc_u32 s47, s45, s17
	s_add_u32 m0, s57, 0x2000
	v_lshl_add_u64 v[144:145], v[136:137], 0, s[46:47]
	global_load_lds_dwordx4 v[144:145], off sc1
	v_mfma_f32_16x16x32_bf16 v[44:47], v[176:179], v[206:209], v[44:47]
	v_mfma_f32_16x16x32_bf16 v[36:39], v[176:179], v[210:213], v[36:39]
	s_add_u32 s46, s44, s18
	s_addc_u32 s47, s45, s19
	s_add_u32 m0, s57, 0x4000
	v_lshl_add_u64 v[144:145], v[136:137], 0, s[46:47]
	global_load_lds_dwordx4 v[144:145], off sc1
	v_mfma_f32_16x16x32_bf16 v[40:43], v[176:179], v[214:217], v[40:43]
	v_mfma_f32_16x16x32_bf16 v[32:35], v[176:179], v[218:221], v[32:35]
	s_add_u32 s46, s44, s22
	s_addc_u32 s47, s45, s23
	s_add_u32 m0, s57, 0x6000
	v_lshl_add_u64 v[144:145], v[136:137], 0, s[46:47]
	global_load_lds_dwordx4 v[144:145], off sc1
	v_mfma_f32_16x16x32_bf16 v[28:31], v[182:185], v[206:209], v[28:31]
	v_mfma_f32_16x16x32_bf16 v[16:19], v[182:185], v[210:213], v[16:19]
	s_add_u32 s46, s44, s30
	s_addc_u32 s47, s45, s31
	s_add_u32 m0, s57, 0x8000
	v_lshl_add_u64 v[144:145], v[134:135], 0, s[46:47]
	global_load_lds_dwordx4 v[144:145], off sc1
	v_mfma_f32_16x16x32_bf16 v[24:27], v[182:185], v[214:217], v[24:27]
	v_mfma_f32_16x16x32_bf16 v[12:15], v[182:185], v[218:221], v[12:15]
	s_add_u32 s46, s44, s36
	s_addc_u32 s47, s45, s37
	s_add_u32 m0, s57, 0xa000
	v_lshl_add_u64 v[144:145], v[134:135], 0, s[46:47]
	global_load_lds_dwordx4 v[144:145], off sc1
	v_mfma_f32_16x16x32_bf16 v[4:7], v[186:189], v[206:209], v[4:7]
	v_mfma_f32_16x16x32_bf16 v[0:3], v[186:189], v[210:213], v[0:3]
	s_add_u32 s46, s44, s38
	s_addc_u32 s47, s45, s39
	s_add_u32 m0, s57, 0xc000
	v_lshl_add_u64 v[144:145], v[134:135], 0, s[46:47]
	global_load_lds_dwordx4 v[144:145], off sc1
	v_mfma_f32_16x16x32_bf16 v[20:23], v[186:189], v[214:217], v[20:23]
	v_mfma_f32_16x16x32_bf16 v[8:11], v[186:189], v[218:221], v[8:11]
	s_add_u32 s46, s44, s40
	s_addc_u32 s47, s45, s41
	s_add_u32 m0, s57, 0xe000
	v_lshl_add_u64 v[144:145], v[134:135], 0, s[46:47]
	global_load_lds_dwordx4 v[144:145], off sc1

.LBB0_1636:
	s_ashr_i32 s20, s44, 2
	v_mov_b32_e32 v6, v181
	s_and_b32 s4, s44, 7
	s_and_b32 s39, s20, -8
	s_or_b32 s30, s39, s4
	v_lshrrev_b32_e32 v7, 4, v6
	v_lshlrev_b32_e32 v1, 6, v6
	v_xor_b32_e32 v0, v7, v6
	v_and_b32_e32 v8, 0x3c0, v1
	v_lshlrev_b32_e32 v1, 8, v6
	s_ashr_i32 s31, s30, 31
	v_lshlrev_b32_e32 v0, 3, v0
	v_and_b32_e32 v1, 0xfffff800, v1
	s_and_b32 s38, s43, 7
	s_bfe_u32 s4, s44, 0x20003
	s_lshl_b64 s[20:21], s[30:31], 20
	v_and_or_b32 v0, v0, 56, v1
	s_add_u32 s20, s3, s20
	v_ashrrev_i32_e32 v1, 31, v0
	s_addc_u32 s21, s40, s21
	v_lshlrev_b64 v[0:1], 1, v[0:1]
	v_lshl_add_u32 v134, v6, 4, 0
	v_lshl_add_u64 v[2:3], s[20:21], 0, v[0:1]
	v_readfirstlane_b32 s20, v134
	v_add_u32_e32 v9, 0x2000, v134
	s_mov_b32 m0, s20
	v_readfirstlane_b32 s20, v9
	v_add_u32_e32 v9, 0x4000, v134
	s_waitcnt vmcnt(63) expcnt(7) lgkmcnt(15)
	s_barrier
	global_load_lds_dwordx4 v[2:3], off
	v_lshl_add_u64 v[4:5], v[2:3], 0, s[6:7]
	s_mov_b32 m0, s20
	v_readfirstlane_b32 s20, v9
	global_load_lds_dwordx4 v[4:5], off
	v_lshl_add_u64 v[4:5], v[2:3], 0, s[8:9]
	s_mov_b32 m0, s20
	s_lshl_b32 s31, s4, 20
	global_load_lds_dwordx4 v[4:5], off
	v_add_u32_e32 v4, 0x6000, v134
	s_add_u32 s36, s41, s31
	v_readfirstlane_b32 s20, v4
	v_add_u32_e32 v4, 0x8000, v134
	s_addc_u32 s37, s42, 0
	v_lshl_add_u64 v[2:3], v[2:3], 0, s[10:11]
	s_mov_b32 m0, s20
	v_readfirstlane_b32 s20, v4
	v_add_u32_e32 v9, 0xa000, v134
	global_load_lds_dwordx4 v[2:3], off
	v_lshl_add_u64 v[2:3], s[36:37], 0, v[0:1]
	s_mov_b32 m0, s20
	v_readfirstlane_b32 s20, v9
	v_add_u32_e32 v9, 0xc000, v134
	global_load_lds_dwordx4 v[2:3], off
	v_lshl_add_u64 v[4:5], v[2:3], 0, s[6:7]
	s_mov_b32 m0, s20
	v_readfirstlane_b32 s20, v9
	global_load_lds_dwordx4 v[4:5], off
	v_lshl_add_u64 v[4:5], v[2:3], 0, s[8:9]
	s_mov_b32 m0, s20
	v_lshl_add_u64 v[2:3], v[2:3], 0, s[10:11]
	global_load_lds_dwordx4 v[4:5], off
	v_add_u32_e32 v4, 0xe000, v134
	v_mov_b32_e32 v36, 0
	v_readfirstlane_b32 s20, v4
	s_mov_b32 m0, s20
	v_ashrrev_i32_e32 v4, 6, v6
	global_load_lds_dwordx4 v[2:3], off
	s_or_b32 s20, s39, s38
	v_lshrrev_b32_e32 v5, 30, v4
	s_ashr_i32 s21, s20, 31
	v_add_u32_e32 v5, v4, v5
	s_lshl_b64 s[20:21], s[20:21], 20
	v_bfe_u32 v2, v6, 4, 2
	v_bfe_u32 v3, v6, 1, 3
	v_and_b32_e32 v6, 0x7fffc, v5
	s_add_u32 s20, s34, s20
	v_sub_u32_e32 v4, v4, v6
	s_addc_u32 s21, s35, s21
	v_lshlrev_b32_e32 v136, 13, v4
	v_bitop3_b32 v4, v7, v3, 3 bitop3:0x6c
	v_bitop3_b32 v2, v2, v3, 4 bitop3:0x36
	v_lshl_add_u64 v[130:131], s[20:21], 0, v[0:1]
	s_add_u32 s20, s34, s31
	v_lshlrev_b32_e32 v5, 12, v5
	v_lshlrev_b32_e32 v4, 3, v4
	v_lshlrev_b32_e32 v2, 3, v2
	s_addc_u32 s21, s35, 0
	v_and_b32_e32 v135, 0xffffc000, v5
	v_lshl_add_u64 v[132:133], s[20:21], 0, v[0:1]
	s_mov_b64 s[36:37], 0
	v_lshlrev_b32_e32 v137, 1, v8
	v_lshlrev_b32_e32 v138, 1, v4
	v_lshlrev_b32_e32 v139, 1, v2
	s_mov_b32 s45, 0
	s_mov_b32 s31, 0
	v_mov_b32_e32 v37, v36
	v_mov_b32_e32 v38, v36
	v_mov_b32_e32 v39, v36
	v_mov_b32_e32 v40, v36
	v_mov_b32_e32 v41, v36
	v_mov_b32_e32 v42, v36
	v_mov_b32_e32 v43, v36
	v_mov_b32_e32 v0, v36
	v_mov_b32_e32 v1, v36
	v_mov_b32_e32 v2, v36
	v_mov_b32_e32 v3, v36
	v_mov_b32_e32 v4, v36
	v_mov_b32_e32 v5, v36
	v_mov_b32_e32 v6, v36
	v_mov_b32_e32 v7, v36
	v_mov_b32_e32 v8, v36
	v_mov_b32_e32 v9, v36
	v_mov_b32_e32 v10, v36
	v_mov_b32_e32 v11, v36
	v_mov_b32_e32 v12, v36
	v_mov_b32_e32 v13, v36
	v_mov_b32_e32 v14, v36
	v_mov_b32_e32 v15, v36
	v_mov_b32_e32 v16, v36
	v_mov_b32_e32 v17, v36
	v_mov_b32_e32 v18, v36
	v_mov_b32_e32 v19, v36
	v_mov_b32_e32 v20, v36
	v_mov_b32_e32 v21, v36
	v_mov_b32_e32 v22, v36
	v_mov_b32_e32 v23, v36
	v_mov_b32_e32 v24, v36
	v_mov_b32_e32 v25, v36
	v_mov_b32_e32 v26, v36
	v_mov_b32_e32 v27, v36
	v_mov_b32_e32 v28, v36
	v_mov_b32_e32 v29, v36
	v_mov_b32_e32 v30, v36
	v_mov_b32_e32 v31, v36
	v_mov_b32_e32 v32, v36
	v_mov_b32_e32 v33, v36
	v_mov_b32_e32 v34, v36
	v_mov_b32_e32 v35, v36
	v_mov_b32_e32 v44, v36
	v_mov_b32_e32 v45, v36
	v_mov_b32_e32 v46, v36
	v_mov_b32_e32 v47, v36
	v_mov_b32_e32 v48, v36
	v_mov_b32_e32 v49, v36
	v_mov_b32_e32 v50, v36
	v_mov_b32_e32 v51, v36
	v_mov_b32_e32 v52, v36
	v_mov_b32_e32 v53, v36
	v_mov_b32_e32 v54, v36
	v_mov_b32_e32 v55, v36
	v_mov_b32_e32 v56, v36
	v_mov_b32_e32 v57, v36
	v_mov_b32_e32 v58, v36
	v_mov_b32_e32 v59, v36
	v_mov_b32_e32 v60, v36
	v_mov_b32_e32 v61, v36
	v_mov_b32_e32 v62, v36
	v_mov_b32_e32 v63, v36
	v_mov_b32_e32 v64, v36
	v_mov_b32_e32 v65, v36
	v_mov_b32_e32 v66, v36
	v_mov_b32_e32 v67, v36
	v_mov_b32_e32 v68, v36
	v_mov_b32_e32 v69, v36
	v_mov_b32_e32 v70, v36
	v_mov_b32_e32 v71, v36
	v_mov_b32_e32 v72, v36
	v_mov_b32_e32 v73, v36
	v_mov_b32_e32 v74, v36
	v_mov_b32_e32 v75, v36
	v_mov_b32_e32 v76, v36
	v_mov_b32_e32 v77, v36
	v_mov_b32_e32 v78, v36
	v_mov_b32_e32 v79, v36
	v_mov_b32_e32 v80, v36
	v_mov_b32_e32 v81, v36
	v_mov_b32_e32 v82, v36
	v_mov_b32_e32 v83, v36
	v_mov_b32_e32 v84, v36
	v_mov_b32_e32 v85, v36
	v_mov_b32_e32 v86, v36
	v_mov_b32_e32 v87, v36
	v_mov_b32_e32 v88, v36
	v_mov_b32_e32 v89, v36
	v_mov_b32_e32 v90, v36
	v_mov_b32_e32 v91, v36
	v_mov_b32_e32 v92, v36
	v_mov_b32_e32 v93, v36
	v_mov_b32_e32 v94, v36
	v_mov_b32_e32 v95, v36
	v_mov_b32_e32 v96, v36
	v_mov_b32_e32 v97, v36
	v_mov_b32_e32 v98, v36
	v_mov_b32_e32 v99, v36
	v_mov_b32_e32 v100, v36
	v_mov_b32_e32 v101, v36
	v_mov_b32_e32 v102, v36
	v_mov_b32_e32 v103, v36
	v_mov_b32_e32 v104, v36
	v_mov_b32_e32 v105, v36
	v_mov_b32_e32 v106, v36
	v_mov_b32_e32 v107, v36
	v_mov_b32_e32 v108, v36
	v_mov_b32_e32 v109, v36
	v_mov_b32_e32 v110, v36
	v_mov_b32_e32 v111, v36
	v_mov_b32_e32 v112, v36
	v_mov_b32_e32 v113, v36
	v_mov_b32_e32 v114, v36
	v_mov_b32_e32 v115, v36
	v_mov_b32_e32 v116, v36
	v_mov_b32_e32 v117, v36
	v_mov_b32_e32 v118, v36
	v_mov_b32_e32 v119, v36
	v_mov_b32_e32 v120, v36
	v_mov_b32_e32 v121, v36
	v_mov_b32_e32 v122, v36
	v_mov_b32_e32 v123, v36
	v_mov_b32_e32 v124, v36
	v_mov_b32_e32 v125, v36
	v_mov_b32_e32 v126, v36
	v_mov_b32_e32 v127, v36
	s_waitcnt vmcnt(0) lgkmcnt(0)
	s_barrier
	v_add3_u32 v141, v135, v137, v138
	v_add3_u32 v210, v136, v137, v138
	v_add3_u32 v180, v135, v137, v139
	v_add3_u32 v211, v136, v137, v139
	v_readfirstlane_b32 s45, v134
	ds_read_b128 v[142:145], v141
	ds_read_b128 v[146:149], v141 offset:2048
	ds_read_b128 v[150:153], v141 offset:4096
	ds_read_b128 v[154:157], v141 offset:6144
	ds_read_b128 v[174:177], v210 offset:32768
	ds_read_b128 v[182:185], v210 offset:34816
	ds_read_b128 v[186:189], v210 offset:36864
	ds_read_b128 v[190:193], v210 offset:38912
	s_mov_b32 s31, 0
	s_mov_b64 s[36:37], 0
	s_add_u32 s45, s45, 0x10000
	s_add_u32 s38, s36, s12
	s_addc_u32 s39, s37, s13
	s_mov_b32 m0, s45
	v_lshl_add_u64 v[178:179], v[130:131], 0, s[38:39]
	global_load_lds_dwordx4 v[178:179], off sc1
	s_add_u32 s38, s36, s14
	s_addc_u32 s39, s37, s15
	s_add_u32 m0, s45, 0x2000
	v_lshl_add_u64 v[178:179], v[130:131], 0, s[38:39]
	global_load_lds_dwordx4 v[178:179], off sc1
	s_add_u32 s38, s36, s16
	s_addc_u32 s39, s37, s17
	s_add_u32 m0, s45, 0x4000
	v_lshl_add_u64 v[178:179], v[130:131], 0, s[38:39]
	global_load_lds_dwordx4 v[178:179], off sc1
	s_add_u32 s38, s36, s18
	s_addc_u32 s39, s37, s19
	s_add_u32 m0, s45, 0x6000
	v_lshl_add_u64 v[178:179], v[130:131], 0, s[38:39]
	global_load_lds_dwordx4 v[178:179], off sc1
	s_add_u32 s38, s36, s22
	s_addc_u32 s39, s37, s23
	s_add_u32 m0, s45, 0x8000
	v_lshl_add_u64 v[178:179], v[132:133], 0, s[38:39]
	global_load_lds_dwordx4 v[178:179], off sc1
	s_add_u32 s38, s36, s24
	s_addc_u32 s39, s37, s25
	s_add_u32 m0, s45, 0xa000
	v_lshl_add_u64 v[178:179], v[132:133], 0, s[38:39]
	global_load_lds_dwordx4 v[178:179], off sc1
	s_add_u32 s38, s36, s26
	s_addc_u32 s39, s37, s27
	s_add_u32 m0, s45, 0xc000
	v_lshl_add_u64 v[178:179], v[132:133], 0, s[38:39]
	global_load_lds_dwordx4 v[178:179], off sc1
	s_add_u32 s38, s36, s28
	s_addc_u32 s39, s37, s29
	s_add_u32 m0, s45, 0xe000
	v_lshl_add_u64 v[178:179], v[132:133], 0, s[38:39]
	global_load_lds_dwordx4 v[178:179], off sc1
	s_branch .Lg11_entry
.Lg11_top:
	s_waitcnt lgkmcnt(0)
	s_waitcnt vmcnt(0)
	s_barrier
	v_xor_b32_e32 v141, 0x10000, v141
	v_xor_b32_e32 v210, 0x10000, v210
	v_xor_b32_e32 v180, 0x10000, v180
	v_xor_b32_e32 v211, 0x10000, v211
	s_xor_b32 s45, s45, 0x10000
	ds_read_b128 v[142:145], v141
	ds_read_b128 v[146:149], v141 offset:2048
	ds_read_b128 v[150:153], v141 offset:4096
	ds_read_b128 v[154:157], v141 offset:6144
	ds_read_b128 v[174:177], v210 offset:32768
	ds_read_b128 v[182:185], v210 offset:34816
	ds_read_b128 v[186:189], v210 offset:36864
	ds_read_b128 v[190:193], v210 offset:38912
	v_mfma_f32_16x16x32_bf16 v[60:63], v[158:161], v[194:197], v[60:63]
	v_mfma_f32_16x16x32_bf16 v[56:59], v[158:161], v[198:201], v[56:59]
	s_add_u32 s38, s36, s12
	s_addc_u32 s39, s37, s13
	s_mov_b32 m0, s45
	v_lshl_add_u64 v[178:179], v[130:131], 0, s[38:39]
	global_load_lds_dwordx4 v[178:179], off sc1
	v_mfma_f32_16x16x32_bf16 v[52:55], v[158:161], v[202:205], v[52:55]
	v_mfma_f32_16x16x32_bf16 v[48:51], v[158:161], v[206:209], v[48:51]
	s_add_u32 s38, s36, s14
	s_addc_u32 s39, s37, s15
	s_add_u32 m0, s45, 0x2000
	v_lshl_add_u64 v[178:179], v[130:131], 0, s[38:39]
	global_load_lds_dwordx4 v[178:179], off sc1
	v_mfma_f32_16x16x32_bf16 v[44:47], v[162:165], v[194:197], v[44:47]
	v_mfma_f32_16x16x32_bf16 v[32:35], v[162:165], v[198:201], v[32:35]
	s_add_u32 s38, s36, s16
	s_addc_u32 s39, s37, s17
	s_add_u32 m0, s45, 0x4000
	v_lshl_add_u64 v[178:179], v[130:131], 0, s[38:39]
	global_load_lds_dwordx4 v[178:179], off sc1
	v_mfma_f32_16x16x32_bf16 v[28:31], v[162:165], v[202:205], v[28:31]
	v_mfma_f32_16x16x32_bf16 v[24:27], v[162:165], v[206:209], v[24:27]
	s_add_u32 s38, s36, s18
	s_addc_u32 s39, s37, s19
	s_add_u32 m0, s45, 0x6000
	v_lshl_add_u64 v[178:179], v[130:131], 0, s[38:39]
	global_load_lds_dwordx4 v[178:179], off sc1
	v_mfma_f32_16x16x32_bf16 v[20:23], v[166:169], v[194:197], v[20:23]
	v_mfma_f32_16x16x32_bf16 v[16:19], v[166:169], v[198:201], v[16:19]
	s_add_u32 s38, s36, s22
	s_addc_u32 s39, s37, s23
	s_add_u32 m0, s45, 0x8000
	v_lshl_add_u64 v[178:179], v[132:133], 0, s[38:39]
	global_load_lds_dwordx4 v[178:179], off sc1
	v_mfma_f32_16x16x32_bf16 v[12:15], v[166:169], v[202:205], v[12:15]
	v_mfma_f32_16x16x32_bf16 v[8:11], v[166:169], v[206:209], v[8:11]
	s_add_u32 s38, s36, s24
	s_addc_u32 s39, s37, s25
	s_add_u32 m0, s45, 0xa000
	v_lshl_add_u64 v[178:179], v[132:133], 0, s[38:39]
	global_load_lds_dwordx4 v[178:179], off sc1
	v_mfma_f32_16x16x32_bf16 v[4:7], v[170:173], v[194:197], v[4:7]
	v_mfma_f32_16x16x32_bf16 v[0:3], v[170:173], v[198:201], v[0:3]
	s_add_u32 s38, s36, s26
	s_addc_u32 s39, s37, s27
	s_add_u32 m0, s45, 0xc000
	v_lshl_add_u64 v[178:179], v[132:133], 0, s[38:39]
	global_load_lds_dwordx4 v[178:179], off sc1
	v_mfma_f32_16x16x32_bf16 v[40:43], v[170:173], v[202:205], v[40:43]
	v_mfma_f32_16x16x32_bf16 v[36:39], v[170:173], v[206:209], v[36:39]
	s_add_u32 s38, s36, s28
	s_addc_u32 s39, s37, s29
	s_add_u32 m0, s45, 0xe000
	v_lshl_add_u64 v[178:179], v[132:133], 0, s[38:39]
	global_load_lds_dwordx4 v[178:179], off sc1
